# counted-wait ladders extended to GLU, branch-A (half 0) and branch-B (half 0) epilogues, on v53
# speedup vs baseline: 1.0099x; 1.0001x over previous
; __device__ __forceinline__ u32x4 pack8(const f32x4 v0, const f32x4 v1) { u32x4 w; w.x = cvt_pk_bf16(v0[0], v0[1]); w.y = cvt_pk_bf16(v0[2], v0[3]); w.z = cvt_pk_bf16(v1[0], v1[1]); w.w = cvt_pk_bf16(v1[2], v1[3]); return w; }
; __device__ __forceinline__ float bf_lo(unsigned w) { return __uint_as_float(w << 16); }
; __device__ __forceinline__ float bf_hi(unsigned w) { return __uint_as_float(w & 0xffff0000u); }
; #define EPI_SIG(v0, v1) do { _Pragma("unroll") for (int e_ = 0; e_ < 4; ++e_) { v0[e_] = sigm(v0[e_]); v1[e_] = sigm(v1[e_]); } } while (0)
;     __device__ __forceinline__ void operator()(const f32x4 (&acc)[2][2][4][2], const Unit& u, int wr, int wc, int fr, int fq) const {
;         u32x4 y[2][4][2]; f32x4 bb[2][2];
;         _Pragma("unroll") for (int bj = 0; bj < 2; ++bj) { const int col = u.pn * BM + EPI_CT(bj); bb[bj][0] = *(const f32x4*)(bias + col); bb[bj][1] = *(const f32x4*)(bias + col + 4); }
;         _Pragma("unroll") for (int ai = 0; ai < 2; ++ai) _Pragma("unroll") for (int m = 0; m < 4; ++m) _Pragma("unroll") for (int bj = 0; bj < 2; ++bj)
;             y[ai][m][bj] = *(const u32x4*)(YB + (size_t)EPI_ROW(ai, m) * 512 + u.pn * BM + EPI_CT(bj));
;         _Pragma("unroll") for (int ai = 0; ai < 2; ++ai) _Pragma("unroll") for (int m = 0; m < 4; ++m) _Pragma("unroll") for (int bj = 0; bj < 2; ++bj) {
;             f32x4 v0 = acc[ai][bj][m][0] + bb[bj][0], v1 = acc[ai][bj][m][1] + bb[bj][1]; const u32x4 yy = y[ai][m][bj]; EPI_SIG(v0, v1);
;             v0[0] *= bf_lo(yy.x); v0[1] *= bf_hi(yy.x); v0[2] *= bf_lo(yy.y); v0[3] *= bf_hi(yy.y); v1[0] *= bf_lo(yy.z); v1[1] *= bf_hi(yy.z); v1[2] *= bf_lo(yy.w); v1[3] *= bf_hi(yy.w);
;             *(u32x4*)(O + (size_t)EPI_ROW(ai, m) * 512 + u.pn * BM + EPI_CT(bj)) = pack8(v0, v1); }
;     }
.LBB0_550:
	s_lshl_b32 s16, s46, 8
	v_or_b32_e32 v74, s16, v210
	v_ashrrev_i32_e32 v75, 31, v74
	v_lshl_add_u64 v[74:75], v[74:75], 2, s[6:7]
	global_load_dwordx4 v[90:93], v[74:75], off
	global_load_dwordx4 v[82:85], v[74:75], off offset:16
	s_ashr_i32 s17, s16, 31
	v_lshl_add_u32 v76, s33, 8, v211
	s_lshl_b64 s[22:23], s[16:17], 1
	v_ashrrev_i32_e32 v77, 31, v76
	s_add_u32 s16, s26, s22
	v_lshlrev_b64 v[216:217], 10, v[76:77]
	s_addc_u32 s17, s27, s23
	v_lshlrev_b32_e32 v0, 1, v210
	v_or_b32_e32 v94, 16, v76
	v_or_b32_e32 v96, 32, v76
	v_or_b32_e32 v98, 48, v76
	v_add_u32_e32 v100, 0x80, v76
	v_add_u32_e32 v110, 0x90, v76
	v_add_u32_e32 v112, 0xa0, v76
	v_add_u32_e32 v114, 0xb0, v76
	v_lshl_add_u64 v[76:77], s[16:17], 0, v[216:217]
	v_lshl_add_u64 v[76:77], v[76:77], 0, v[0:1]
	global_load_dwordx4 v[212:215], v[76:77], off
	v_ashrrev_i32_e32 v95, 31, v94
	v_ashrrev_i32_e32 v97, 31, v96
	v_ashrrev_i32_e32 v99, 31, v98
	v_ashrrev_i32_e32 v101, 31, v100
	v_lshlrev_b64 v[236:237], 10, v[94:95]
	v_lshlrev_b64 v[234:235], 10, v[96:97]
	v_lshlrev_b64 v[232:233], 10, v[98:99]
	v_lshlrev_b64 v[230:231], 10, v[100:101]
	global_load_dwordx4 v[94:97], v[74:75], off offset:528
	global_load_dwordx4 v[98:101], v[74:75], off offset:512
	v_ashrrev_i32_e32 v111, 31, v110
	v_ashrrev_i32_e32 v113, 31, v112
	v_ashrrev_i32_e32 v115, 31, v114
	v_lshlrev_b64 v[228:229], 10, v[110:111]
	v_lshlrev_b64 v[226:227], 10, v[112:113]
	v_lshlrev_b64 v[224:225], 10, v[114:115]
	v_lshl_add_u64 v[74:75], s[16:17], 0, v[236:237]
	v_lshl_add_u64 v[110:111], s[16:17], 0, v[234:235]
	v_lshl_add_u64 v[112:113], s[16:17], 0, v[232:233]
	v_lshl_add_u64 v[114:115], s[16:17], 0, v[230:231]
	v_lshl_add_u64 v[116:117], s[16:17], 0, v[228:229]
	v_lshl_add_u64 v[130:131], s[16:17], 0, v[226:227]
	v_lshl_add_u64 v[132:133], s[16:17], 0, v[224:225]
	v_lshl_add_u64 v[74:75], v[74:75], 0, v[0:1]
	v_lshl_add_u64 v[110:111], v[110:111], 0, v[0:1]
	v_lshl_add_u64 v[112:113], v[112:113], 0, v[0:1]
	v_lshl_add_u64 v[114:115], v[114:115], 0, v[0:1]
	v_lshl_add_u64 v[116:117], v[116:117], 0, v[0:1]
	v_lshl_add_u64 v[218:219], v[130:131], 0, v[0:1]
	v_lshl_add_u64 v[238:239], v[132:133], 0, v[0:1]
	global_load_dwordx4 v[246:249], v[76:77], off offset:256
	global_load_dwordx4 v[198:201], v[74:75], off
	global_load_dwordx4 v[194:197], v[74:75], off offset:256
	global_load_dwordx4 v[190:193], v[110:111], off
	global_load_dwordx4 v[186:189], v[110:111], off offset:256
	global_load_dwordx4 v[182:185], v[112:113], off
	global_load_dwordx4 v[178:181], v[112:113], off offset:256
	global_load_dwordx4 v[174:177], v[114:115], off
	global_load_dwordx4 v[162:165], v[114:115], off offset:256
	global_load_dwordx4 v[150:153], v[116:117], off
	global_load_dwordx4 v[138:141], v[116:117], off offset:256
	global_load_dwordx4 v[130:133], v[218:219], off
	s_nop 0
	global_load_dwordx4 v[114:117], v[218:219], off offset:256
	global_load_dwordx4 v[110:113], v[238:239], off
	global_load_dwordx4 v[74:77], v[238:239], off offset:256
	s_andn2_b64 vcc, exec, s[4:5]
	s_mov_b64 s[4:5], -1
	s_waitcnt vmcnt(15)
	v_pk_add_f32 v[170:171], v[170:171], v[90:91]
	v_pk_add_f32 v[172:173], v[172:173], v[92:93]
	v_pk_add_f32 v[168:169], v[168:169], v[84:85]
	v_pk_add_f32 v[166:167], v[166:167], v[82:83]
	v_mul_f32_e32 v170, 0xbfb8aa3b, v170
	v_mul_f32_e32 v166, 0xbfb8aa3b, v166
	v_mul_f32_e32 v172, 0xbfb8aa3b, v172
	v_mul_f32_e32 v168, 0xbfb8aa3b, v168
	v_exp_f32_e32 v170, v170
	v_exp_f32_e32 v166, v166
	v_exp_f32_e32 v172, v172
	v_exp_f32_e32 v218, v168
	v_mul_f32_e32 v173, 0xbfb8aa3b, v173
	v_mul_f32_e32 v171, 0xbfb8aa3b, v171
	v_mul_f32_e32 v167, 0xbfb8aa3b, v167
	v_exp_f32_e32 v173, v173
	v_exp_f32_e32 v171, v171
	v_exp_f32_e32 v167, v167
	v_add_f32_e32 v168, 1.0, v170
	v_mul_f32_e32 v169, 0xbfb8aa3b, v169
	v_add_f32_e32 v170, 1.0, v166
	v_rcp_f32_e32 v166, v168
	v_add_f32_e32 v168, 1.0, v172
	v_add_f32_e32 v172, 1.0, v218
	v_exp_f32_e32 v218, v169
	v_add_f32_e32 v169, 1.0, v173
	v_add_f32_e32 v171, 1.0, v171
	v_add_f32_e32 v219, 1.0, v167
	v_rcp_f32_e32 v168, v168
	v_rcp_f32_e32 v169, v169
	v_rcp_f32_e32 v170, v170
	v_rcp_f32_e32 v167, v171
	v_rcp_f32_e32 v171, v219
	v_add_f32_e32 v173, 1.0, v218
	v_rcp_f32_e32 v172, v172
	v_rcp_f32_e32 v173, v173
	v_lshlrev_b32_e32 v218, 16, v212
	v_and_b32_e32 v219, 0xffff0000, v212
	v_lshlrev_b32_e32 v212, 16, v213
	v_and_b32_e32 v213, 0xffff0000, v213
	v_pk_mul_f32 v[168:169], v[168:169], v[212:213]
	v_lshlrev_b32_e32 v212, 16, v214
	v_and_b32_e32 v213, 0xffff0000, v214
	v_pk_mul_f32 v[166:167], v[166:167], v[218:219]
	v_pk_mul_f32 v[170:171], v[170:171], v[212:213]
	v_lshlrev_b32_e32 v212, 16, v215
	v_and_b32_e32 v213, 0xffff0000, v215
	v_cvt_pk_bf16_f32 v166, v166, v167
	v_cvt_pk_bf16_f32 v167, v168, v169
	v_cvt_pk_bf16_f32 v168, v170, v171
	v_lshl_add_u64 v[170:171], s[8:9], 0, v[216:217]
	v_pk_mul_f32 v[172:173], v[172:173], v[212:213]
	v_lshl_add_u64 v[170:171], v[170:171], 0, s[22:23]
	v_pk_add_f32 v[158:159], v[158:159], v[98:99]
	v_pk_add_f32 v[154:155], v[154:155], v[94:95]
	v_cvt_pk_bf16_f32 v169, v172, v173
	v_lshl_add_u64 v[170:171], v[170:171], 0, v[0:1]
	v_mul_f32_e32 v158, 0xbfb8aa3b, v158
	v_mul_f32_e32 v154, 0xbfb8aa3b, v154
	global_store_dwordx4 v[170:171], v[166:169], off
	s_waitcnt vmcnt(15)
; __device__ __forceinline__ u32x4 pack8(const f32x4 v0, const f32x4 v1) { u32x4 w; w.x = cvt_pk_bf16(v0[0], v0[1]); w.y = cvt_pk_bf16(v0[2], v0[3]); w.z = cvt_pk_bf16(v1[0], v1[1]); w.w = cvt_pk_bf16(v1[2], v1[3]); return w; }
; __device__ __forceinline__ float bf_lo(unsigned w) { return __uint_as_float(w << 16); }
; __device__ __forceinline__ float bf_hi(unsigned w) { return __uint_as_float(w & 0xffff0000u); }
; #define EPI_SIG(v0, v1) do { _Pragma("unroll") for (int e_ = 0; e_ < 4; ++e_) { v0[e_] = sigm(v0[e_]); v1[e_] = sigm(v1[e_]); } } while (0)
;     __device__ __forceinline__ void operator()(const f32x4 (&acc)[2][2][4][2], const Unit& u, int wr, int wc, int fr, int fq) const {
;     ...
;         _Pragma("unroll") for (int ai = 0; ai < 2; ++ai) _Pragma("unroll") for (int m = 0; m < 4; ++m) _Pragma("unroll") for (int bj = 0; bj < 2; ++bj) {
;             f32x4 v0 = acc[ai][bj][m][0] + bb[bj][0], v1 = acc[ai][bj][m][1] + bb[bj][1]; const u32x4 yy = y[ai][m][bj]; EPI_SIG(v0, v1);
;             v0[0] *= bf_lo(yy.x); v0[1] *= bf_hi(yy.x); v0[2] *= bf_lo(yy.y); v0[3] *= bf_hi(yy.y); v1[0] *= bf_lo(yy.z); v1[1] *= bf_hi(yy.z); v1[2] *= bf_lo(yy.w); v1[3] *= bf_hi(yy.w);
;             *(u32x4*)(O + (size_t)EPI_ROW(ai, m) * 512 + u.pn * BM + EPI_CT(bj)) = pack8(v0, v1); }
	v_exp_f32_e32 v158, v158
	v_mul_f32_e32 v159, 0xbfb8aa3b, v159
	v_exp_f32_e32 v166, v154
	v_mul_f32_e32 v155, 0xbfb8aa3b, v155
	v_add_f32_e32 v154, 1.0, v158
	v_exp_f32_e32 v159, v159
	v_add_f32_e32 v158, 1.0, v166
	v_exp_f32_e32 v166, v155
	v_pk_add_f32 v[160:161], v[160:161], v[100:101]
	v_pk_add_f32 v[156:157], v[156:157], v[96:97]
	v_mul_f32_e32 v160, 0xbfb8aa3b, v160
	v_mul_f32_e32 v156, 0xbfb8aa3b, v156
	v_add_f32_e32 v155, 1.0, v159
	v_add_f32_e32 v159, 1.0, v166
	v_exp_f32_e32 v160, v160
	v_exp_f32_e32 v166, v156
	v_mul_f32_e32 v161, 0xbfb8aa3b, v161
	v_exp_f32_e32 v161, v161
	v_mul_f32_e32 v157, 0xbfb8aa3b, v157
	v_add_f32_e32 v156, 1.0, v160
	v_add_f32_e32 v160, 1.0, v166
	v_exp_f32_e32 v166, v157
	v_rcp_f32_e32 v154, v154
	v_rcp_f32_e32 v155, v155
	v_add_f32_e32 v157, 1.0, v161
	v_rcp_f32_e32 v156, v156
	v_rcp_f32_e32 v157, v157
	v_rcp_f32_e32 v158, v158
	v_rcp_f32_e32 v159, v159
	v_add_f32_e32 v161, 1.0, v166
	v_rcp_f32_e32 v160, v160
	v_rcp_f32_e32 v161, v161
	v_lshlrev_b32_e32 v166, 16, v246
	v_and_b32_e32 v167, 0xffff0000, v246
	v_pk_mul_f32 v[154:155], v[154:155], v[166:167]
	v_lshlrev_b32_e32 v166, 16, v247
	v_and_b32_e32 v167, 0xffff0000, v247
	v_pk_mul_f32 v[156:157], v[156:157], v[166:167]
	v_lshlrev_b32_e32 v166, 16, v248
	v_and_b32_e32 v167, 0xffff0000, v248
	v_pk_mul_f32 v[158:159], v[158:159], v[166:167]
	v_lshlrev_b32_e32 v166, 16, v249
	v_and_b32_e32 v167, 0xffff0000, v249
	v_pk_mul_f32 v[160:161], v[160:161], v[166:167]
	v_pk_add_f32 v[146:147], v[146:147], v[90:91]
	v_pk_add_f32 v[142:143], v[142:143], v[82:83]
	v_cvt_pk_bf16_f32 v154, v154, v155
	v_cvt_pk_bf16_f32 v155, v156, v157
	v_cvt_pk_bf16_f32 v156, v158, v159
	v_cvt_pk_bf16_f32 v157, v160, v161
	v_mul_f32_e32 v146, 0xbfb8aa3b, v146
	v_mul_f32_e32 v142, 0xbfb8aa3b, v142
	global_store_dwordx4 v[170:171], v[154:157], off offset:256
	s_waitcnt vmcnt(15)
	v_exp_f32_e32 v146, v146
	v_mul_f32_e32 v147, 0xbfb8aa3b, v147
	v_exp_f32_e32 v154, v142
	v_mul_f32_e32 v143, 0xbfb8aa3b, v143
	v_add_f32_e32 v142, 1.0, v146
	v_exp_f32_e32 v147, v147
	v_add_f32_e32 v146, 1.0, v154
	v_exp_f32_e32 v154, v143
	v_pk_add_f32 v[148:149], v[148:149], v[92:93]
	v_pk_add_f32 v[144:145], v[144:145], v[84:85]
	v_mul_f32_e32 v148, 0xbfb8aa3b, v148
	v_mul_f32_e32 v144, 0xbfb8aa3b, v144
	v_add_f32_e32 v143, 1.0, v147
	v_add_f32_e32 v147, 1.0, v154
	v_exp_f32_e32 v148, v148
	v_exp_f32_e32 v154, v144
	v_mul_f32_e32 v149, 0xbfb8aa3b, v149
	v_exp_f32_e32 v149, v149
	v_mul_f32_e32 v145, 0xbfb8aa3b, v145
	v_add_f32_e32 v144, 1.0, v148
	v_add_f32_e32 v148, 1.0, v154
	v_exp_f32_e32 v154, v145
	v_rcp_f32_e32 v142, v142
	v_rcp_f32_e32 v143, v143
	v_add_f32_e32 v145, 1.0, v149
	v_rcp_f32_e32 v144, v144
	v_rcp_f32_e32 v145, v145
	v_rcp_f32_e32 v146, v146
	v_rcp_f32_e32 v147, v147
	v_add_f32_e32 v149, 1.0, v154
	v_lshlrev_b32_e32 v154, 16, v198
	v_and_b32_e32 v155, 0xffff0000, v198
	v_rcp_f32_e32 v148, v148
	v_rcp_f32_e32 v149, v149
	v_pk_mul_f32 v[142:143], v[142:143], v[154:155]
	v_lshlrev_b32_e32 v154, 16, v199
	v_and_b32_e32 v155, 0xffff0000, v199
	v_pk_mul_f32 v[144:145], v[144:145], v[154:155]
	v_lshlrev_b32_e32 v154, 16, v200
	v_and_b32_e32 v155, 0xffff0000, v200
	v_pk_mul_f32 v[146:147], v[146:147], v[154:155]
	v_lshlrev_b32_e32 v154, 16, v201
	v_and_b32_e32 v155, 0xffff0000, v201
	v_cvt_pk_bf16_f32 v142, v142, v143
	v_cvt_pk_bf16_f32 v143, v144, v145
	v_cvt_pk_bf16_f32 v144, v146, v147
	v_lshl_add_u64 v[146:147], s[8:9], 0, v[236:237]
	v_pk_mul_f32 v[148:149], v[148:149], v[154:155]
	v_lshl_add_u64 v[146:147], v[146:147], 0, s[22:23]
	v_pk_add_f32 v[134:135], v[134:135], v[98:99]
	v_pk_add_f32 v[126:127], v[126:127], v[94:95]
	v_cvt_pk_bf16_f32 v145, v148, v149
	v_lshl_add_u64 v[146:147], v[146:147], 0, v[0:1]
	v_mul_f32_e32 v134, 0xbfb8aa3b, v134
	v_mul_f32_e32 v126, 0xbfb8aa3b, v126
	global_store_dwordx4 v[146:147], v[142:145], off
	s_waitcnt vmcnt(15)
	v_exp_f32_e32 v134, v134
	v_mul_f32_e32 v135, 0xbfb8aa3b, v135
	v_exp_f32_e32 v142, v126
	v_mul_f32_e32 v127, 0xbfb8aa3b, v127
	v_add_f32_e32 v126, 1.0, v134
	v_exp_f32_e32 v135, v135
	v_add_f32_e32 v134, 1.0, v142
	v_exp_f32_e32 v142, v127
	v_pk_add_f32 v[136:137], v[136:137], v[100:101]
	v_pk_add_f32 v[128:129], v[128:129], v[96:97]
	v_mul_f32_e32 v136, 0xbfb8aa3b, v136
	v_mul_f32_e32 v128, 0xbfb8aa3b, v128
	v_add_f32_e32 v127, 1.0, v135
	v_add_f32_e32 v135, 1.0, v142
	v_exp_f32_e32 v136, v136
	v_exp_f32_e32 v142, v128
	v_mul_f32_e32 v137, 0xbfb8aa3b, v137
	v_exp_f32_e32 v137, v137
	v_mul_f32_e32 v129, 0xbfb8aa3b, v129
	v_add_f32_e32 v128, 1.0, v136
	v_add_f32_e32 v136, 1.0, v142
	v_exp_f32_e32 v142, v129
	v_rcp_f32_e32 v126, v126
	v_rcp_f32_e32 v127, v127
	v_add_f32_e32 v129, 1.0, v137
	v_rcp_f32_e32 v128, v128
	v_rcp_f32_e32 v129, v129
	v_rcp_f32_e32 v134, v134
	v_rcp_f32_e32 v135, v135
	v_add_f32_e32 v137, 1.0, v142
	v_rcp_f32_e32 v136, v136
	v_rcp_f32_e32 v137, v137
	v_lshlrev_b32_e32 v142, 16, v194
	v_and_b32_e32 v143, 0xffff0000, v194
	v_pk_mul_f32 v[126:127], v[126:127], v[142:143]
	v_lshlrev_b32_e32 v142, 16, v195
	v_and_b32_e32 v143, 0xffff0000, v195
	v_pk_mul_f32 v[128:129], v[128:129], v[142:143]
	v_lshlrev_b32_e32 v142, 16, v196
	v_and_b32_e32 v143, 0xffff0000, v196
	v_pk_mul_f32 v[134:135], v[134:135], v[142:143]
	v_lshlrev_b32_e32 v142, 16, v197
	v_and_b32_e32 v143, 0xffff0000, v197
	v_pk_mul_f32 v[136:137], v[136:137], v[142:143]
	v_pk_add_f32 v[122:123], v[122:123], v[90:91]
	v_pk_add_f32 v[118:119], v[118:119], v[82:83]
	v_cvt_pk_bf16_f32 v126, v126, v127
	v_cvt_pk_bf16_f32 v127, v128, v129
	v_cvt_pk_bf16_f32 v128, v134, v135
	v_cvt_pk_bf16_f32 v129, v136, v137
	v_mul_f32_e32 v122, 0xbfb8aa3b, v122
	v_mul_f32_e32 v118, 0xbfb8aa3b, v118
	global_store_dwordx4 v[146:147], v[126:129], off offset:256
	s_waitcnt vmcnt(15)
; __device__ __forceinline__ u32x4 pack8(const f32x4 v0, const f32x4 v1) { u32x4 w; w.x = cvt_pk_bf16(v0[0], v0[1]); w.y = cvt_pk_bf16(v0[2], v0[3]); w.z = cvt_pk_bf16(v1[0], v1[1]); w.w = cvt_pk_bf16(v1[2], v1[3]); return w; }
; __device__ __forceinline__ float bf_lo(unsigned w) { return __uint_as_float(w << 16); }
; __device__ __forceinline__ float bf_hi(unsigned w) { return __uint_as_float(w & 0xffff0000u); }
; #define EPI_SIG(v0, v1) do { _Pragma("unroll") for (int e_ = 0; e_ < 4; ++e_) { v0[e_] = sigm(v0[e_]); v1[e_] = sigm(v1[e_]); } } while (0)
;     __device__ __forceinline__ void operator()(const f32x4 (&acc)[2][2][4][2], const Unit& u, int wr, int wc, int fr, int fq) const {
;     ...
;         _Pragma("unroll") for (int ai = 0; ai < 2; ++ai) _Pragma("unroll") for (int m = 0; m < 4; ++m) _Pragma("unroll") for (int bj = 0; bj < 2; ++bj) {
;             f32x4 v0 = acc[ai][bj][m][0] + bb[bj][0], v1 = acc[ai][bj][m][1] + bb[bj][1]; const u32x4 yy = y[ai][m][bj]; EPI_SIG(v0, v1);
;             v0[0] *= bf_lo(yy.x); v0[1] *= bf_hi(yy.x); v0[2] *= bf_lo(yy.y); v0[3] *= bf_hi(yy.y); v1[0] *= bf_lo(yy.z); v1[1] *= bf_hi(yy.z); v1[2] *= bf_lo(yy.w); v1[3] *= bf_hi(yy.w);
;             *(u32x4*)(O + (size_t)EPI_ROW(ai, m) * 512 + u.pn * BM + EPI_CT(bj)) = pack8(v0, v1); }
	v_exp_f32_e32 v122, v122
	v_mul_f32_e32 v123, 0xbfb8aa3b, v123
	v_exp_f32_e32 v126, v118
	v_mul_f32_e32 v119, 0xbfb8aa3b, v119
	v_add_f32_e32 v118, 1.0, v122
	v_exp_f32_e32 v123, v123
	v_add_f32_e32 v122, 1.0, v126
	v_exp_f32_e32 v126, v119
	v_pk_add_f32 v[124:125], v[124:125], v[92:93]
	v_pk_add_f32 v[120:121], v[120:121], v[84:85]
	v_mul_f32_e32 v124, 0xbfb8aa3b, v124
	v_mul_f32_e32 v120, 0xbfb8aa3b, v120
	v_add_f32_e32 v119, 1.0, v123
	v_add_f32_e32 v123, 1.0, v126
	v_exp_f32_e32 v124, v124
	v_exp_f32_e32 v126, v120
	v_mul_f32_e32 v125, 0xbfb8aa3b, v125
	v_exp_f32_e32 v125, v125
	v_mul_f32_e32 v121, 0xbfb8aa3b, v121
	v_add_f32_e32 v120, 1.0, v124
	v_add_f32_e32 v124, 1.0, v126
	v_exp_f32_e32 v126, v121
	v_rcp_f32_e32 v118, v118
	v_rcp_f32_e32 v119, v119
	v_add_f32_e32 v121, 1.0, v125
	v_rcp_f32_e32 v120, v120
	v_rcp_f32_e32 v121, v121
	v_rcp_f32_e32 v122, v122
	v_rcp_f32_e32 v123, v123
	v_add_f32_e32 v125, 1.0, v126
	v_lshlrev_b32_e32 v126, 16, v190
	v_and_b32_e32 v127, 0xffff0000, v190
	v_rcp_f32_e32 v124, v124
	v_rcp_f32_e32 v125, v125
	v_pk_mul_f32 v[118:119], v[118:119], v[126:127]
	v_lshlrev_b32_e32 v126, 16, v191
	v_and_b32_e32 v127, 0xffff0000, v191
	v_pk_mul_f32 v[120:121], v[120:121], v[126:127]
	v_lshlrev_b32_e32 v126, 16, v192
	v_and_b32_e32 v127, 0xffff0000, v192
	v_pk_mul_f32 v[122:123], v[122:123], v[126:127]
	v_lshlrev_b32_e32 v126, 16, v193
	v_and_b32_e32 v127, 0xffff0000, v193
	v_cvt_pk_bf16_f32 v118, v118, v119
	v_cvt_pk_bf16_f32 v119, v120, v121
	v_cvt_pk_bf16_f32 v120, v122, v123
	v_lshl_add_u64 v[122:123], s[8:9], 0, v[234:235]
	v_pk_mul_f32 v[124:125], v[124:125], v[126:127]
	v_lshl_add_u64 v[122:123], v[122:123], 0, s[22:23]
	v_pk_add_f32 v[106:107], v[106:107], v[98:99]
	v_pk_add_f32 v[102:103], v[102:103], v[94:95]
	v_cvt_pk_bf16_f32 v121, v124, v125
	v_lshl_add_u64 v[122:123], v[122:123], 0, v[0:1]
	v_mul_f32_e32 v106, 0xbfb8aa3b, v106
	v_mul_f32_e32 v102, 0xbfb8aa3b, v102
	global_store_dwordx4 v[122:123], v[118:121], off
	s_waitcnt vmcnt(15)
	v_exp_f32_e32 v106, v106
	v_mul_f32_e32 v107, 0xbfb8aa3b, v107
	v_exp_f32_e32 v118, v102
	v_mul_f32_e32 v103, 0xbfb8aa3b, v103
	v_add_f32_e32 v102, 1.0, v106
	v_exp_f32_e32 v107, v107
	v_add_f32_e32 v106, 1.0, v118
	v_exp_f32_e32 v118, v103
	v_pk_add_f32 v[108:109], v[108:109], v[100:101]
	v_pk_add_f32 v[104:105], v[104:105], v[96:97]
	v_mul_f32_e32 v108, 0xbfb8aa3b, v108
	v_mul_f32_e32 v104, 0xbfb8aa3b, v104
	v_add_f32_e32 v103, 1.0, v107
	v_add_f32_e32 v107, 1.0, v118
	v_exp_f32_e32 v108, v108
	v_exp_f32_e32 v118, v104
	v_mul_f32_e32 v109, 0xbfb8aa3b, v109
	v_exp_f32_e32 v109, v109
	v_mul_f32_e32 v105, 0xbfb8aa3b, v105
	v_add_f32_e32 v104, 1.0, v108
	v_add_f32_e32 v108, 1.0, v118
	v_exp_f32_e32 v118, v105
	v_rcp_f32_e32 v102, v102
	v_rcp_f32_e32 v103, v103
	v_add_f32_e32 v105, 1.0, v109
	v_rcp_f32_e32 v104, v104
	v_rcp_f32_e32 v105, v105
	v_rcp_f32_e32 v106, v106
	v_rcp_f32_e32 v107, v107
	v_add_f32_e32 v109, 1.0, v118
	v_rcp_f32_e32 v108, v108
	v_rcp_f32_e32 v109, v109
	v_lshlrev_b32_e32 v118, 16, v186
	v_and_b32_e32 v119, 0xffff0000, v186
	v_pk_mul_f32 v[102:103], v[102:103], v[118:119]
	v_lshlrev_b32_e32 v118, 16, v187
	v_and_b32_e32 v119, 0xffff0000, v187
	v_pk_mul_f32 v[104:105], v[104:105], v[118:119]
	v_lshlrev_b32_e32 v118, 16, v188
	v_and_b32_e32 v119, 0xffff0000, v188
	v_pk_mul_f32 v[106:107], v[106:107], v[118:119]
	v_lshlrev_b32_e32 v118, 16, v189
	v_and_b32_e32 v119, 0xffff0000, v189
	v_pk_mul_f32 v[108:109], v[108:109], v[118:119]
	v_pk_add_f32 v[86:87], v[86:87], v[90:91]
	v_pk_add_f32 v[78:79], v[78:79], v[82:83]
	v_cvt_pk_bf16_f32 v102, v102, v103
	v_cvt_pk_bf16_f32 v103, v104, v105
	v_cvt_pk_bf16_f32 v104, v106, v107
	v_cvt_pk_bf16_f32 v105, v108, v109
	v_mul_f32_e32 v86, 0xbfb8aa3b, v86
	v_mul_f32_e32 v78, 0xbfb8aa3b, v78
	global_store_dwordx4 v[122:123], v[102:105], off offset:256
	s_waitcnt vmcnt(15)
	v_exp_f32_e32 v86, v86
	v_mul_f32_e32 v87, 0xbfb8aa3b, v87
	v_exp_f32_e32 v102, v78
	v_mul_f32_e32 v79, 0xbfb8aa3b, v79
	v_add_f32_e32 v78, 1.0, v86
	v_exp_f32_e32 v87, v87
	v_add_f32_e32 v86, 1.0, v102
	v_exp_f32_e32 v102, v79
	v_pk_add_f32 v[88:89], v[88:89], v[92:93]
	v_pk_add_f32 v[80:81], v[80:81], v[84:85]
	v_mul_f32_e32 v88, 0xbfb8aa3b, v88
	v_mul_f32_e32 v80, 0xbfb8aa3b, v80
	v_add_f32_e32 v79, 1.0, v87
	v_add_f32_e32 v87, 1.0, v102
	v_exp_f32_e32 v88, v88
	v_exp_f32_e32 v102, v80
	v_mul_f32_e32 v89, 0xbfb8aa3b, v89
	v_exp_f32_e32 v89, v89
	v_mul_f32_e32 v81, 0xbfb8aa3b, v81
	v_add_f32_e32 v80, 1.0, v88
	v_add_f32_e32 v88, 1.0, v102
	v_exp_f32_e32 v102, v81
	v_rcp_f32_e32 v78, v78
	v_rcp_f32_e32 v79, v79
	v_add_f32_e32 v81, 1.0, v89
	v_rcp_f32_e32 v80, v80
	v_rcp_f32_e32 v81, v81
	v_rcp_f32_e32 v86, v86
	v_rcp_f32_e32 v87, v87
	v_add_f32_e32 v89, 1.0, v102
	v_lshlrev_b32_e32 v102, 16, v182
	v_and_b32_e32 v103, 0xffff0000, v182
	v_rcp_f32_e32 v88, v88
	v_rcp_f32_e32 v89, v89
	v_pk_mul_f32 v[78:79], v[78:79], v[102:103]
	v_lshlrev_b32_e32 v102, 16, v183
	v_and_b32_e32 v103, 0xffff0000, v183
	v_pk_mul_f32 v[80:81], v[80:81], v[102:103]
	v_lshlrev_b32_e32 v102, 16, v184
	v_and_b32_e32 v103, 0xffff0000, v184
	v_pk_mul_f32 v[86:87], v[86:87], v[102:103]
	v_lshlrev_b32_e32 v102, 16, v185
	v_and_b32_e32 v103, 0xffff0000, v185
	v_cvt_pk_bf16_f32 v78, v78, v79
	v_cvt_pk_bf16_f32 v79, v80, v81
	v_cvt_pk_bf16_f32 v80, v86, v87
	v_lshl_add_u64 v[86:87], s[8:9], 0, v[232:233]
	v_pk_mul_f32 v[88:89], v[88:89], v[102:103]
	v_lshl_add_u64 v[86:87], v[86:87], 0, s[22:23]
	v_pk_add_f32 v[70:71], v[70:71], v[98:99]
	v_pk_add_f32 v[66:67], v[66:67], v[94:95]
	v_cvt_pk_bf16_f32 v81, v88, v89
	v_lshl_add_u64 v[86:87], v[86:87], 0, v[0:1]
	v_mul_f32_e32 v70, 0xbfb8aa3b, v70
	v_mul_f32_e32 v66, 0xbfb8aa3b, v66
	global_store_dwordx4 v[86:87], v[78:81], off
	s_waitcnt vmcnt(15)
; __device__ __forceinline__ u32x4 pack8(const f32x4 v0, const f32x4 v1) { u32x4 w; w.x = cvt_pk_bf16(v0[0], v0[1]); w.y = cvt_pk_bf16(v0[2], v0[3]); w.z = cvt_pk_bf16(v1[0], v1[1]); w.w = cvt_pk_bf16(v1[2], v1[3]); return w; }
; __device__ __forceinline__ float bf_lo(unsigned w) { return __uint_as_float(w << 16); }
; __device__ __forceinline__ float bf_hi(unsigned w) { return __uint_as_float(w & 0xffff0000u); }
; #define EPI_SIG(v0, v1) do { _Pragma("unroll") for (int e_ = 0; e_ < 4; ++e_) { v0[e_] = sigm(v0[e_]); v1[e_] = sigm(v1[e_]); } } while (0)
;     __device__ __forceinline__ void operator()(const f32x4 (&acc)[2][2][4][2], const Unit& u, int wr, int wc, int fr, int fq) const {
;     ...
;         _Pragma("unroll") for (int ai = 0; ai < 2; ++ai) _Pragma("unroll") for (int m = 0; m < 4; ++m) _Pragma("unroll") for (int bj = 0; bj < 2; ++bj) {
;             f32x4 v0 = acc[ai][bj][m][0] + bb[bj][0], v1 = acc[ai][bj][m][1] + bb[bj][1]; const u32x4 yy = y[ai][m][bj]; EPI_SIG(v0, v1);
;             v0[0] *= bf_lo(yy.x); v0[1] *= bf_hi(yy.x); v0[2] *= bf_lo(yy.y); v0[3] *= bf_hi(yy.y); v1[0] *= bf_lo(yy.z); v1[1] *= bf_hi(yy.z); v1[2] *= bf_lo(yy.w); v1[3] *= bf_hi(yy.w);
;             *(u32x4*)(O + (size_t)EPI_ROW(ai, m) * 512 + u.pn * BM + EPI_CT(bj)) = pack8(v0, v1); }
	v_exp_f32_e32 v70, v70
	v_mul_f32_e32 v71, 0xbfb8aa3b, v71
	v_exp_f32_e32 v78, v66
	v_mul_f32_e32 v67, 0xbfb8aa3b, v67
	v_add_f32_e32 v66, 1.0, v70
	v_exp_f32_e32 v71, v71
	v_add_f32_e32 v70, 1.0, v78
	v_exp_f32_e32 v78, v67
	v_pk_add_f32 v[72:73], v[72:73], v[100:101]
	v_pk_add_f32 v[68:69], v[68:69], v[96:97]
	v_mul_f32_e32 v72, 0xbfb8aa3b, v72
	v_mul_f32_e32 v68, 0xbfb8aa3b, v68
	v_add_f32_e32 v67, 1.0, v71
	v_add_f32_e32 v71, 1.0, v78
	v_exp_f32_e32 v72, v72
	v_exp_f32_e32 v78, v68
	v_mul_f32_e32 v73, 0xbfb8aa3b, v73
	v_exp_f32_e32 v73, v73
	v_mul_f32_e32 v69, 0xbfb8aa3b, v69
	v_add_f32_e32 v68, 1.0, v72
	v_add_f32_e32 v72, 1.0, v78
	v_exp_f32_e32 v78, v69
	v_rcp_f32_e32 v66, v66
	v_rcp_f32_e32 v67, v67
	v_add_f32_e32 v69, 1.0, v73
	v_rcp_f32_e32 v68, v68
	v_rcp_f32_e32 v69, v69
	v_rcp_f32_e32 v70, v70
	v_rcp_f32_e32 v71, v71
	v_add_f32_e32 v73, 1.0, v78
	v_rcp_f32_e32 v72, v72
	v_rcp_f32_e32 v73, v73
	v_lshlrev_b32_e32 v78, 16, v178
	v_and_b32_e32 v79, 0xffff0000, v178
	v_pk_mul_f32 v[66:67], v[66:67], v[78:79]
	v_lshlrev_b32_e32 v78, 16, v179
	v_and_b32_e32 v79, 0xffff0000, v179
	v_pk_mul_f32 v[68:69], v[68:69], v[78:79]
	v_lshlrev_b32_e32 v78, 16, v180
	v_and_b32_e32 v79, 0xffff0000, v180
	v_pk_mul_f32 v[70:71], v[70:71], v[78:79]
	v_lshlrev_b32_e32 v78, 16, v181
	v_and_b32_e32 v79, 0xffff0000, v181
	v_pk_mul_f32 v[72:73], v[72:73], v[78:79]
	v_pk_add_f32 v[62:63], v[62:63], v[90:91]
	v_pk_add_f32 v[58:59], v[58:59], v[82:83]
	v_cvt_pk_bf16_f32 v66, v66, v67
	v_cvt_pk_bf16_f32 v67, v68, v69
	v_cvt_pk_bf16_f32 v68, v70, v71
	v_cvt_pk_bf16_f32 v69, v72, v73
	v_mul_f32_e32 v62, 0xbfb8aa3b, v62
	v_mul_f32_e32 v58, 0xbfb8aa3b, v58
	global_store_dwordx4 v[86:87], v[66:69], off offset:256
	s_waitcnt vmcnt(15)
	v_exp_f32_e32 v62, v62
	v_mul_f32_e32 v63, 0xbfb8aa3b, v63
	v_exp_f32_e32 v66, v58
	v_mul_f32_e32 v59, 0xbfb8aa3b, v59
	v_add_f32_e32 v58, 1.0, v62
	v_exp_f32_e32 v63, v63
	v_add_f32_e32 v62, 1.0, v66
	v_exp_f32_e32 v66, v59
	v_pk_add_f32 v[64:65], v[64:65], v[92:93]
	v_pk_add_f32 v[60:61], v[60:61], v[84:85]
	v_mul_f32_e32 v64, 0xbfb8aa3b, v64
	v_mul_f32_e32 v60, 0xbfb8aa3b, v60
	v_add_f32_e32 v59, 1.0, v63
	v_add_f32_e32 v63, 1.0, v66
	v_exp_f32_e32 v64, v64
	v_exp_f32_e32 v66, v60
	v_mul_f32_e32 v65, 0xbfb8aa3b, v65
	v_exp_f32_e32 v65, v65
	v_mul_f32_e32 v61, 0xbfb8aa3b, v61
	v_add_f32_e32 v60, 1.0, v64
	v_add_f32_e32 v64, 1.0, v66
	v_exp_f32_e32 v66, v61
	v_rcp_f32_e32 v58, v58
	v_rcp_f32_e32 v59, v59
	v_add_f32_e32 v61, 1.0, v65
	v_rcp_f32_e32 v60, v60
	v_rcp_f32_e32 v61, v61
	v_rcp_f32_e32 v62, v62
	v_rcp_f32_e32 v63, v63
	v_add_f32_e32 v65, 1.0, v66
	v_lshlrev_b32_e32 v66, 16, v174
	v_and_b32_e32 v67, 0xffff0000, v174
	v_rcp_f32_e32 v64, v64
	v_rcp_f32_e32 v65, v65
	v_pk_mul_f32 v[58:59], v[58:59], v[66:67]
	v_lshlrev_b32_e32 v66, 16, v175
	v_and_b32_e32 v67, 0xffff0000, v175
	v_pk_mul_f32 v[60:61], v[60:61], v[66:67]
	v_lshlrev_b32_e32 v66, 16, v176
	v_and_b32_e32 v67, 0xffff0000, v176
	v_pk_mul_f32 v[62:63], v[62:63], v[66:67]
	v_lshlrev_b32_e32 v66, 16, v177
	v_and_b32_e32 v67, 0xffff0000, v177
	v_cvt_pk_bf16_f32 v58, v58, v59
	v_cvt_pk_bf16_f32 v59, v60, v61
	v_cvt_pk_bf16_f32 v60, v62, v63
	v_lshl_add_u64 v[62:63], s[8:9], 0, v[230:231]
	v_pk_mul_f32 v[64:65], v[64:65], v[66:67]
	v_lshl_add_u64 v[62:63], v[62:63], 0, s[22:23]
	v_pk_add_f32 v[54:55], v[54:55], v[98:99]
	v_pk_add_f32 v[50:51], v[50:51], v[94:95]
	v_cvt_pk_bf16_f32 v61, v64, v65
	v_lshl_add_u64 v[62:63], v[62:63], 0, v[0:1]
	v_mul_f32_e32 v54, 0xbfb8aa3b, v54
	v_mul_f32_e32 v50, 0xbfb8aa3b, v50
	global_store_dwordx4 v[62:63], v[58:61], off
	s_waitcnt vmcnt(15)
	v_exp_f32_e32 v54, v54
	v_mul_f32_e32 v55, 0xbfb8aa3b, v55
	v_exp_f32_e32 v58, v50
	v_mul_f32_e32 v51, 0xbfb8aa3b, v51
	v_add_f32_e32 v50, 1.0, v54
	v_exp_f32_e32 v55, v55
	v_add_f32_e32 v54, 1.0, v58
	v_exp_f32_e32 v58, v51
	v_pk_add_f32 v[56:57], v[56:57], v[100:101]
	v_pk_add_f32 v[52:53], v[52:53], v[96:97]
	v_mul_f32_e32 v56, 0xbfb8aa3b, v56
	v_mul_f32_e32 v52, 0xbfb8aa3b, v52
	v_add_f32_e32 v51, 1.0, v55
	v_add_f32_e32 v55, 1.0, v58
	v_exp_f32_e32 v56, v56
	v_exp_f32_e32 v58, v52
	v_mul_f32_e32 v57, 0xbfb8aa3b, v57
	v_exp_f32_e32 v57, v57
	v_mul_f32_e32 v53, 0xbfb8aa3b, v53
	v_add_f32_e32 v52, 1.0, v56
	v_add_f32_e32 v56, 1.0, v58
	v_exp_f32_e32 v58, v53
	v_rcp_f32_e32 v50, v50
	v_rcp_f32_e32 v51, v51
	v_add_f32_e32 v53, 1.0, v57
	v_rcp_f32_e32 v52, v52
	v_rcp_f32_e32 v53, v53
	v_rcp_f32_e32 v54, v54
	v_rcp_f32_e32 v55, v55
	v_add_f32_e32 v57, 1.0, v58
	v_rcp_f32_e32 v56, v56
	v_rcp_f32_e32 v57, v57
	v_lshlrev_b32_e32 v58, 16, v162
	v_and_b32_e32 v59, 0xffff0000, v162
	v_pk_mul_f32 v[50:51], v[50:51], v[58:59]
	v_lshlrev_b32_e32 v58, 16, v163
	v_and_b32_e32 v59, 0xffff0000, v163
	v_pk_mul_f32 v[52:53], v[52:53], v[58:59]
	v_lshlrev_b32_e32 v58, 16, v164
	v_and_b32_e32 v59, 0xffff0000, v164
	v_pk_mul_f32 v[54:55], v[54:55], v[58:59]
	v_lshlrev_b32_e32 v58, 16, v165
	v_and_b32_e32 v59, 0xffff0000, v165
	v_pk_mul_f32 v[56:57], v[56:57], v[58:59]
	v_pk_add_f32 v[46:47], v[46:47], v[90:91]
	v_pk_add_f32 v[42:43], v[42:43], v[82:83]
	v_cvt_pk_bf16_f32 v50, v50, v51
	v_cvt_pk_bf16_f32 v51, v52, v53
	v_cvt_pk_bf16_f32 v52, v54, v55
	v_cvt_pk_bf16_f32 v53, v56, v57
	v_mul_f32_e32 v46, 0xbfb8aa3b, v46
	v_mul_f32_e32 v42, 0xbfb8aa3b, v42
	global_store_dwordx4 v[62:63], v[50:53], off offset:256
	s_waitcnt vmcnt(15)
; __device__ __forceinline__ u32x4 pack8(const f32x4 v0, const f32x4 v1) { u32x4 w; w.x = cvt_pk_bf16(v0[0], v0[1]); w.y = cvt_pk_bf16(v0[2], v0[3]); w.z = cvt_pk_bf16(v1[0], v1[1]); w.w = cvt_pk_bf16(v1[2], v1[3]); return w; }
; __device__ __forceinline__ float bf_lo(unsigned w) { return __uint_as_float(w << 16); }
; __device__ __forceinline__ float bf_hi(unsigned w) { return __uint_as_float(w & 0xffff0000u); }
; #define EPI_SIG(v0, v1) do { _Pragma("unroll") for (int e_ = 0; e_ < 4; ++e_) { v0[e_] = sigm(v0[e_]); v1[e_] = sigm(v1[e_]); } } while (0)
; __device__ __forceinline__ float sigm(float x) { return __builtin_amdgcn_rcpf(1.0f + __builtin_amdgcn_exp2f(-x * LOG2E)); }
;     __device__ __forceinline__ void operator()(const f32x4 (&acc)[2][2][4][2], const Unit& u, int wr, int wc, int fr, int fq) const {
;     ...
;         _Pragma("unroll") for (int ai = 0; ai < 2; ++ai) _Pragma("unroll") for (int m = 0; m < 4; ++m) _Pragma("unroll") for (int bj = 0; bj < 2; ++bj) {
;             f32x4 v0 = acc[ai][bj][m][0] + bb[bj][0], v1 = acc[ai][bj][m][1] + bb[bj][1]; const u32x4 yy = y[ai][m][bj]; EPI_SIG(v0, v1);
;             v0[0] *= bf_lo(yy.x); v0[1] *= bf_hi(yy.x); v0[2] *= bf_lo(yy.y); v0[3] *= bf_hi(yy.y); v1[0] *= bf_lo(yy.z); v1[1] *= bf_hi(yy.z); v1[2] *= bf_lo(yy.w); v1[3] *= bf_hi(yy.w);
;             *(u32x4*)(O + (size_t)EPI_ROW(ai, m) * 512 + u.pn * BM + EPI_CT(bj)) = pack8(v0, v1); }
	v_exp_f32_e32 v46, v46
	v_mul_f32_e32 v47, 0xbfb8aa3b, v47
	v_exp_f32_e32 v50, v42
	v_mul_f32_e32 v43, 0xbfb8aa3b, v43
	v_add_f32_e32 v42, 1.0, v46
	v_exp_f32_e32 v47, v47
	v_add_f32_e32 v46, 1.0, v50
	v_exp_f32_e32 v50, v43
	v_pk_add_f32 v[48:49], v[48:49], v[92:93]
	v_pk_add_f32 v[44:45], v[44:45], v[84:85]
	v_mul_f32_e32 v48, 0xbfb8aa3b, v48
	v_mul_f32_e32 v44, 0xbfb8aa3b, v44
	v_add_f32_e32 v43, 1.0, v47
	v_add_f32_e32 v47, 1.0, v50
	v_exp_f32_e32 v48, v48
	v_exp_f32_e32 v50, v44
	v_mul_f32_e32 v49, 0xbfb8aa3b, v49
	v_exp_f32_e32 v49, v49
	v_mul_f32_e32 v45, 0xbfb8aa3b, v45
	v_add_f32_e32 v44, 1.0, v48
	v_add_f32_e32 v48, 1.0, v50
	v_exp_f32_e32 v50, v45
	v_rcp_f32_e32 v42, v42
	v_rcp_f32_e32 v43, v43
	v_add_f32_e32 v45, 1.0, v49
	v_rcp_f32_e32 v44, v44
	v_rcp_f32_e32 v45, v45
	v_rcp_f32_e32 v46, v46
	v_rcp_f32_e32 v47, v47
	v_add_f32_e32 v49, 1.0, v50
	v_lshlrev_b32_e32 v50, 16, v150
	v_and_b32_e32 v51, 0xffff0000, v150
	v_rcp_f32_e32 v48, v48
	v_rcp_f32_e32 v49, v49
	v_pk_mul_f32 v[42:43], v[42:43], v[50:51]
	v_lshlrev_b32_e32 v50, 16, v151
	v_and_b32_e32 v51, 0xffff0000, v151
	v_pk_mul_f32 v[44:45], v[44:45], v[50:51]
	v_lshlrev_b32_e32 v50, 16, v152
	v_and_b32_e32 v51, 0xffff0000, v152
	v_pk_mul_f32 v[46:47], v[46:47], v[50:51]
	v_lshlrev_b32_e32 v50, 16, v153
	v_and_b32_e32 v51, 0xffff0000, v153
	v_cvt_pk_bf16_f32 v42, v42, v43
	v_cvt_pk_bf16_f32 v43, v44, v45
	v_cvt_pk_bf16_f32 v44, v46, v47
	v_lshl_add_u64 v[46:47], s[8:9], 0, v[228:229]
	v_pk_mul_f32 v[48:49], v[48:49], v[50:51]
	v_lshl_add_u64 v[46:47], v[46:47], 0, s[22:23]
	v_pk_add_f32 v[38:39], v[38:39], v[98:99]
	v_pk_add_f32 v[34:35], v[34:35], v[94:95]
	v_cvt_pk_bf16_f32 v45, v48, v49
	v_lshl_add_u64 v[46:47], v[46:47], 0, v[0:1]
	v_mul_f32_e32 v38, 0xbfb8aa3b, v38
	v_mul_f32_e32 v34, 0xbfb8aa3b, v34
	global_store_dwordx4 v[46:47], v[42:45], off
	s_waitcnt vmcnt(15)
	v_exp_f32_e32 v38, v38
	v_mul_f32_e32 v39, 0xbfb8aa3b, v39
	v_exp_f32_e32 v42, v34
	v_mul_f32_e32 v35, 0xbfb8aa3b, v35
	v_add_f32_e32 v34, 1.0, v38
	v_exp_f32_e32 v39, v39
	v_add_f32_e32 v38, 1.0, v42
	v_exp_f32_e32 v42, v35
	v_pk_add_f32 v[40:41], v[40:41], v[100:101]
	v_pk_add_f32 v[36:37], v[36:37], v[96:97]
	v_mul_f32_e32 v40, 0xbfb8aa3b, v40
	v_mul_f32_e32 v36, 0xbfb8aa3b, v36
	v_add_f32_e32 v35, 1.0, v39
	v_add_f32_e32 v39, 1.0, v42
	v_exp_f32_e32 v40, v40
	v_exp_f32_e32 v42, v36
	v_mul_f32_e32 v41, 0xbfb8aa3b, v41
	v_exp_f32_e32 v41, v41
	v_mul_f32_e32 v37, 0xbfb8aa3b, v37
	v_add_f32_e32 v36, 1.0, v40
	v_add_f32_e32 v40, 1.0, v42
	v_exp_f32_e32 v42, v37
	v_rcp_f32_e32 v34, v34
	v_rcp_f32_e32 v35, v35
	v_add_f32_e32 v37, 1.0, v41
	v_rcp_f32_e32 v36, v36
	v_rcp_f32_e32 v37, v37
	v_rcp_f32_e32 v38, v38
	v_rcp_f32_e32 v39, v39
	v_add_f32_e32 v41, 1.0, v42
	v_rcp_f32_e32 v40, v40
	v_rcp_f32_e32 v41, v41
	v_lshlrev_b32_e32 v42, 16, v138
	v_and_b32_e32 v43, 0xffff0000, v138
	v_pk_mul_f32 v[34:35], v[34:35], v[42:43]
	v_lshlrev_b32_e32 v42, 16, v139
	v_and_b32_e32 v43, 0xffff0000, v139
	v_pk_mul_f32 v[36:37], v[36:37], v[42:43]
	v_lshlrev_b32_e32 v42, 16, v140
	v_and_b32_e32 v43, 0xffff0000, v140
	v_pk_mul_f32 v[38:39], v[38:39], v[42:43]
	v_lshlrev_b32_e32 v42, 16, v141
	v_and_b32_e32 v43, 0xffff0000, v141
	v_pk_mul_f32 v[40:41], v[40:41], v[42:43]
	v_pk_add_f32 v[30:31], v[30:31], v[90:91]
	v_pk_add_f32 v[26:27], v[26:27], v[82:83]
	v_cvt_pk_bf16_f32 v34, v34, v35
	v_cvt_pk_bf16_f32 v35, v36, v37
	v_cvt_pk_bf16_f32 v36, v38, v39
	v_cvt_pk_bf16_f32 v37, v40, v41
	v_mul_f32_e32 v30, 0xbfb8aa3b, v30
	v_mul_f32_e32 v26, 0xbfb8aa3b, v26
	global_store_dwordx4 v[46:47], v[34:37], off offset:256
	s_waitcnt vmcnt(15)
	v_exp_f32_e32 v30, v30
	v_mul_f32_e32 v31, 0xbfb8aa3b, v31
	v_exp_f32_e32 v34, v26
	v_mul_f32_e32 v27, 0xbfb8aa3b, v27
	v_add_f32_e32 v26, 1.0, v30
	v_exp_f32_e32 v31, v31
	v_add_f32_e32 v30, 1.0, v34
	v_exp_f32_e32 v34, v27
	v_pk_add_f32 v[32:33], v[32:33], v[92:93]
	v_pk_add_f32 v[28:29], v[28:29], v[84:85]
	v_mul_f32_e32 v32, 0xbfb8aa3b, v32
	v_mul_f32_e32 v28, 0xbfb8aa3b, v28
	v_add_f32_e32 v27, 1.0, v31
	v_add_f32_e32 v31, 1.0, v34
	v_exp_f32_e32 v32, v32
	v_exp_f32_e32 v34, v28
	v_mul_f32_e32 v33, 0xbfb8aa3b, v33
	v_exp_f32_e32 v33, v33
	v_mul_f32_e32 v29, 0xbfb8aa3b, v29
	v_add_f32_e32 v28, 1.0, v32
	v_add_f32_e32 v32, 1.0, v34
	v_exp_f32_e32 v34, v29
	v_rcp_f32_e32 v26, v26
	v_rcp_f32_e32 v27, v27
	v_add_f32_e32 v29, 1.0, v33
	v_rcp_f32_e32 v28, v28
	v_rcp_f32_e32 v29, v29
	v_rcp_f32_e32 v30, v30
	v_rcp_f32_e32 v31, v31
	v_add_f32_e32 v33, 1.0, v34
	v_lshlrev_b32_e32 v34, 16, v130
	v_and_b32_e32 v35, 0xffff0000, v130
	v_rcp_f32_e32 v32, v32
	v_rcp_f32_e32 v33, v33
	v_pk_mul_f32 v[26:27], v[26:27], v[34:35]
	v_lshlrev_b32_e32 v34, 16, v131
	v_and_b32_e32 v35, 0xffff0000, v131
	v_pk_mul_f32 v[28:29], v[28:29], v[34:35]
	v_lshlrev_b32_e32 v34, 16, v132
	v_and_b32_e32 v35, 0xffff0000, v132
	v_pk_mul_f32 v[30:31], v[30:31], v[34:35]
	v_lshlrev_b32_e32 v34, 16, v133
	v_and_b32_e32 v35, 0xffff0000, v133
	v_cvt_pk_bf16_f32 v26, v26, v27
	v_cvt_pk_bf16_f32 v27, v28, v29
	v_cvt_pk_bf16_f32 v28, v30, v31
	v_lshl_add_u64 v[30:31], s[8:9], 0, v[226:227]
	v_pk_mul_f32 v[32:33], v[32:33], v[34:35]
	v_lshl_add_u64 v[30:31], v[30:31], 0, s[22:23]
	v_pk_add_f32 v[22:23], v[22:23], v[98:99]
	v_pk_add_f32 v[18:19], v[18:19], v[94:95]
	v_cvt_pk_bf16_f32 v29, v32, v33
	v_lshl_add_u64 v[30:31], v[30:31], 0, v[0:1]
	v_mul_f32_e32 v22, 0xbfb8aa3b, v22
	v_mul_f32_e32 v18, 0xbfb8aa3b, v18
	global_store_dwordx4 v[30:31], v[26:29], off
	s_waitcnt vmcnt(15)
; __device__ __forceinline__ u32x4 pack8(const f32x4 v0, const f32x4 v1) { u32x4 w; w.x = cvt_pk_bf16(v0[0], v0[1]); w.y = cvt_pk_bf16(v0[2], v0[3]); w.z = cvt_pk_bf16(v1[0], v1[1]); w.w = cvt_pk_bf16(v1[2], v1[3]); return w; }
; __device__ __forceinline__ float bf_lo(unsigned w) { return __uint_as_float(w << 16); }
; __device__ __forceinline__ float bf_hi(unsigned w) { return __uint_as_float(w & 0xffff0000u); }
; #define EPI_SIG(v0, v1) do { _Pragma("unroll") for (int e_ = 0; e_ < 4; ++e_) { v0[e_] = sigm(v0[e_]); v1[e_] = sigm(v1[e_]); } } while (0)
; __device__ __forceinline__ float sigm(float x) { return __builtin_amdgcn_rcpf(1.0f + __builtin_amdgcn_exp2f(-x * LOG2E)); }
;     __device__ __forceinline__ void operator()(const f32x4 (&acc)[2][2][4][2], const Unit& u, int wr, int wc, int fr, int fq) const {
;     ...
;         _Pragma("unroll") for (int ai = 0; ai < 2; ++ai) _Pragma("unroll") for (int m = 0; m < 4; ++m) _Pragma("unroll") for (int bj = 0; bj < 2; ++bj) {
;             f32x4 v0 = acc[ai][bj][m][0] + bb[bj][0], v1 = acc[ai][bj][m][1] + bb[bj][1]; const u32x4 yy = y[ai][m][bj]; EPI_SIG(v0, v1);
;             v0[0] *= bf_lo(yy.x); v0[1] *= bf_hi(yy.x); v0[2] *= bf_lo(yy.y); v0[3] *= bf_hi(yy.y); v1[0] *= bf_lo(yy.z); v1[1] *= bf_hi(yy.z); v1[2] *= bf_lo(yy.w); v1[3] *= bf_hi(yy.w);
;             *(u32x4*)(O + (size_t)EPI_ROW(ai, m) * 512 + u.pn * BM + EPI_CT(bj)) = pack8(v0, v1); }
	v_exp_f32_e32 v22, v22
	v_mul_f32_e32 v23, 0xbfb8aa3b, v23
	v_exp_f32_e32 v26, v18
	v_mul_f32_e32 v19, 0xbfb8aa3b, v19
	v_add_f32_e32 v18, 1.0, v22
	v_exp_f32_e32 v23, v23
	v_add_f32_e32 v22, 1.0, v26
	v_exp_f32_e32 v26, v19
	v_pk_add_f32 v[24:25], v[24:25], v[100:101]
	v_pk_add_f32 v[20:21], v[20:21], v[96:97]
	v_mul_f32_e32 v24, 0xbfb8aa3b, v24
	v_mul_f32_e32 v20, 0xbfb8aa3b, v20
	v_add_f32_e32 v19, 1.0, v23
	v_add_f32_e32 v23, 1.0, v26
	v_exp_f32_e32 v24, v24
	v_exp_f32_e32 v26, v20
	v_mul_f32_e32 v25, 0xbfb8aa3b, v25
	v_exp_f32_e32 v25, v25
	v_mul_f32_e32 v21, 0xbfb8aa3b, v21
	v_add_f32_e32 v20, 1.0, v24
	v_add_f32_e32 v24, 1.0, v26
	v_exp_f32_e32 v26, v21
	v_rcp_f32_e32 v18, v18
	v_rcp_f32_e32 v19, v19
	v_add_f32_e32 v21, 1.0, v25
	v_rcp_f32_e32 v20, v20
	v_rcp_f32_e32 v21, v21
	v_rcp_f32_e32 v22, v22
	v_rcp_f32_e32 v23, v23
	v_add_f32_e32 v25, 1.0, v26
	v_rcp_f32_e32 v24, v24
	v_rcp_f32_e32 v25, v25
	v_lshlrev_b32_e32 v26, 16, v114
	v_and_b32_e32 v27, 0xffff0000, v114
	v_pk_mul_f32 v[18:19], v[18:19], v[26:27]
	v_lshlrev_b32_e32 v26, 16, v115
	v_and_b32_e32 v27, 0xffff0000, v115
	v_pk_mul_f32 v[20:21], v[20:21], v[26:27]
	v_lshlrev_b32_e32 v26, 16, v116
	v_and_b32_e32 v27, 0xffff0000, v116
	v_pk_mul_f32 v[22:23], v[22:23], v[26:27]
	v_lshlrev_b32_e32 v26, 16, v117
	v_and_b32_e32 v27, 0xffff0000, v117
	v_pk_mul_f32 v[24:25], v[24:25], v[26:27]
	v_pk_add_f32 v[14:15], v[14:15], v[90:91]
	v_pk_add_f32 v[10:11], v[10:11], v[82:83]
	v_cvt_pk_bf16_f32 v18, v18, v19
	v_cvt_pk_bf16_f32 v19, v20, v21
	v_cvt_pk_bf16_f32 v20, v22, v23
	v_cvt_pk_bf16_f32 v21, v24, v25
	v_mul_f32_e32 v14, 0xbfb8aa3b, v14
	v_mul_f32_e32 v10, 0xbfb8aa3b, v10
	global_store_dwordx4 v[30:31], v[18:21], off offset:256
	s_waitcnt vmcnt(15)
	v_exp_f32_e32 v14, v14
	v_mul_f32_e32 v15, 0xbfb8aa3b, v15
	v_exp_f32_e32 v18, v10
	v_mul_f32_e32 v11, 0xbfb8aa3b, v11
	v_add_f32_e32 v10, 1.0, v14
	v_exp_f32_e32 v15, v15
	v_add_f32_e32 v14, 1.0, v18
	v_exp_f32_e32 v18, v11
	v_pk_add_f32 v[16:17], v[16:17], v[92:93]
	v_pk_add_f32 v[12:13], v[12:13], v[84:85]
	v_mul_f32_e32 v16, 0xbfb8aa3b, v16
	v_mul_f32_e32 v12, 0xbfb8aa3b, v12
	v_add_f32_e32 v11, 1.0, v15
	v_add_f32_e32 v15, 1.0, v18
	v_exp_f32_e32 v16, v16
	v_exp_f32_e32 v18, v12
	v_mul_f32_e32 v17, 0xbfb8aa3b, v17
	v_exp_f32_e32 v17, v17
	v_mul_f32_e32 v13, 0xbfb8aa3b, v13
	v_add_f32_e32 v12, 1.0, v16
	v_add_f32_e32 v16, 1.0, v18
	v_exp_f32_e32 v18, v13
	v_rcp_f32_e32 v10, v10
	v_rcp_f32_e32 v11, v11
	v_add_f32_e32 v13, 1.0, v17
	v_rcp_f32_e32 v12, v12
	v_rcp_f32_e32 v13, v13
	v_rcp_f32_e32 v14, v14
	v_rcp_f32_e32 v15, v15
	v_add_f32_e32 v17, 1.0, v18
	v_lshlrev_b32_e32 v18, 16, v110
	v_and_b32_e32 v19, 0xffff0000, v110
	v_pk_mul_f32 v[10:11], v[10:11], v[18:19]
	v_lshlrev_b32_e32 v18, 16, v111
	v_and_b32_e32 v19, 0xffff0000, v111
	v_pk_mul_f32 v[12:13], v[12:13], v[18:19]
	v_lshlrev_b32_e32 v18, 16, v112
	v_and_b32_e32 v19, 0xffff0000, v112
	v_pk_mul_f32 v[14:15], v[14:15], v[18:19]
	v_cvt_pk_bf16_f32 v10, v10, v11
	v_cvt_pk_bf16_f32 v11, v12, v13
	v_cvt_pk_bf16_f32 v12, v14, v15
	v_lshl_add_u64 v[14:15], s[8:9], 0, v[224:225]
	v_lshl_add_u64 v[14:15], v[14:15], 0, s[22:23]
	v_pk_add_f32 v[6:7], v[6:7], v[98:99]
	v_lshl_add_u64 v[14:15], v[14:15], 0, v[0:1]
	v_pk_add_f32 v[2:3], v[2:3], v[94:95]
	v_mul_f32_e32 v0, 0xbfb8aa3b, v6
	v_exp_f32_e32 v0, v0
	v_mul_f32_e32 v2, 0xbfb8aa3b, v2
	v_exp_f32_e32 v6, v2
	v_rcp_f32_e32 v16, v16
	v_rcp_f32_e32 v17, v17
	v_add_f32_e32 v0, 1.0, v0
	v_rcp_f32_e32 v2, v0
	v_add_f32_e32 v0, 1.0, v6
	v_mul_f32_e32 v6, 0xbfb8aa3b, v7
	v_exp_f32_e32 v7, v6
	v_lshlrev_b32_e32 v18, 16, v113
	v_and_b32_e32 v19, 0xffff0000, v113
	v_pk_mul_f32 v[16:17], v[16:17], v[18:19]
	v_pk_add_f32 v[8:9], v[8:9], v[100:101]
	v_cvt_pk_bf16_f32 v13, v16, v17
	v_mul_f32_e32 v3, 0xbfb8aa3b, v3
	global_store_dwordx4 v[14:15], v[10:13], off
	s_waitcnt vmcnt(15)
	v_rcp_f32_e32 v6, v0
	v_add_f32_e32 v0, 1.0, v7
	v_exp_f32_e32 v10, v3
	v_mul_f32_e32 v7, 0xbfb8aa3b, v8
	v_exp_f32_e32 v8, v7
	v_pk_add_f32 v[4:5], v[4:5], v[96:97]
	v_rcp_f32_e32 v3, v0
	v_mul_f32_e32 v4, 0xbfb8aa3b, v4
	v_add_f32_e32 v0, 1.0, v10
	v_exp_f32_e32 v10, v4
	v_rcp_f32_e32 v7, v0
	v_add_f32_e32 v0, 1.0, v8
	v_mul_f32_e32 v8, 0xbfb8aa3b, v9
	v_exp_f32_e32 v9, v8
	v_mul_f32_e32 v5, 0xbfb8aa3b, v5
	v_rcp_f32_e32 v4, v0
	v_add_f32_e32 v0, 1.0, v10
	v_exp_f32_e32 v10, v5
	v_rcp_f32_e32 v8, v0
	v_add_f32_e32 v0, 1.0, v9
	v_rcp_f32_e32 v5, v0
	v_add_f32_e32 v0, 1.0, v10
	v_rcp_f32_e32 v9, v0
	v_lshlrev_b32_e32 v10, 16, v74
	v_and_b32_e32 v11, 0xffff0000, v74
	v_pk_mul_f32 v[2:3], v[2:3], v[10:11]
	v_lshlrev_b32_e32 v10, 16, v75
	v_and_b32_e32 v11, 0xffff0000, v75
	v_pk_mul_f32 v[4:5], v[4:5], v[10:11]
	v_lshlrev_b32_e32 v10, 16, v76
	v_and_b32_e32 v11, 0xffff0000, v76
	v_pk_mul_f32 v[6:7], v[6:7], v[10:11]
	v_lshlrev_b32_e32 v10, 16, v77
	v_and_b32_e32 v11, 0xffff0000, v77
	v_pk_mul_f32 v[8:9], v[8:9], v[10:11]
	v_cvt_pk_bf16_f32 v2, v2, v3
	v_cvt_pk_bf16_f32 v3, v4, v5
	v_cvt_pk_bf16_f32 v4, v6, v7
	v_cvt_pk_bf16_f32 v5, v8, v9
	global_store_dwordx4 v[14:15], v[2:5], off offset:256
	s_cbranch_vccnz .LBB0_539
	s_andn2_b64 vcc, exec, s[0:1]
	s_cbranch_vccnz .LBB0_538
	s_branch .LBB0_538

; __device__ __forceinline__ u32x4 pack8(const f32x4 v0, const f32x4 v1) { u32x4 w; w.x = cvt_pk_bf16(v0[0], v0[1]); w.y = cvt_pk_bf16(v0[2], v0[3]); w.z = cvt_pk_bf16(v1[0], v1[1]); w.w = cvt_pk_bf16(v1[2], v1[3]); return w; }
; __device__ __forceinline__ float bf_lo(unsigned w) { return __uint_as_float(w << 16); }
; __device__ __forceinline__ float bf_hi(unsigned w) { return __uint_as_float(w & 0xffff0000u); }
;     __device__ __forceinline__ void operator()(const f32x4 (&acc)[2][2][4][2], const Unit& u, int wr, int wc, int fr, int fq) const {
;         _Pragma("unroll") for (int ai = 0; ai < 2; ++ai) {
;             u32x4 gt[4][2], oo[4][2];
;             _Pragma("unroll") for (int m = 0; m < 4; ++m) _Pragma("unroll") for (int bj = 0; bj < 2; ++bj) { const size_t off = (size_t)EPI_ROW(ai, m) * 1024 + u.pn * BM + EPI_CT(bj);
;                 gt[m][bj] = *(const u32x4*)(G + off); if (ADD) oo[m][bj] = *(const u32x4*)(O + off); }
;             _Pragma("unroll") for (int m = 0; m < 4; ++m) _Pragma("unroll") for (int bj = 0; bj < 2; ++bj) { const size_t off = (size_t)EPI_ROW(ai, m) * 1024 + u.pn * BM + EPI_CT(bj);
;                 f32x4 v0 = acc[ai][bj][m][0], v1 = acc[ai][bj][m][1]; const u32x4 g4 = gt[m][bj];
;                 v0[0] *= bf_lo(g4.x); v0[1] *= bf_hi(g4.x); v0[2] *= bf_lo(g4.y); v0[3] *= bf_hi(g4.y); v1[0] *= bf_lo(g4.z); v1[1] *= bf_hi(g4.z); v1[2] *= bf_lo(g4.w); v1[3] *= bf_hi(g4.w);
;                 if (ADD) { const u32x4 o = oo[m][bj];
;                     v0[0] += bf_lo(o.x); v0[1] += bf_hi(o.x); v0[2] += bf_lo(o.y); v0[3] += bf_hi(o.y); v1[0] += bf_lo(o.z); v1[1] += bf_hi(o.z); v1[2] += bf_lo(o.w); v1[3] += bf_hi(o.w); }
;                 *(u32x4*)(O + off) = pack8(v0, v1); }
.LBB0_570:
	s_lshl_b32 s16, s39, 8
	s_ashr_i32 s17, s16, 31
	v_lshl_add_u32 v162, s46, 8, v170
	s_lshl_b64 s[20:21], s[16:17], 1
	s_add_u32 s22, s35, s20
	v_ashrrev_i32_e32 v163, 31, v162
	s_addc_u32 s23, s36, s21
	v_lshlrev_b64 v[186:187], 11, v[162:163]
	v_lshl_add_u64 v[130:131], s[22:23], 0, v[186:187]
	v_lshl_add_u64 v[130:131], v[130:131], 0, v[0:1]
	global_load_dwordx4 v[174:177], v[130:131], off
	global_load_dwordx4 v[178:181], v[130:131], off offset:256
	v_or_b32_e32 v130, 16, v162
	v_ashrrev_i32_e32 v131, 31, v130
	v_lshlrev_b64 v[168:169], 11, v[130:131]
	v_lshl_add_u64 v[130:131], s[22:23], 0, v[168:169]
	v_lshl_add_u64 v[130:131], v[130:131], 0, v[0:1]
	global_load_dwordx4 v[182:185], v[130:131], off
	global_load_dwordx4 v[146:149], v[130:131], off offset:256
	v_or_b32_e32 v130, 32, v162
	v_ashrrev_i32_e32 v131, 31, v130
	v_lshlrev_b64 v[166:167], 11, v[130:131]
	v_lshl_add_u64 v[130:131], s[22:23], 0, v[166:167]
	v_lshl_add_u64 v[130:131], v[130:131], 0, v[0:1]
	global_load_dwordx4 v[142:145], v[130:131], off
	global_load_dwordx4 v[134:137], v[130:131], off offset:256
	v_or_b32_e32 v130, 48, v162
	v_ashrrev_i32_e32 v131, 31, v130
	v_lshlrev_b64 v[164:165], 11, v[130:131]
	v_lshl_add_u64 v[130:131], s[22:23], 0, v[164:165]
	v_lshl_add_u64 v[130:131], v[130:131], 0, v[0:1]
	global_load_dwordx4 v[138:141], v[130:131], off
	s_nop 0
	global_load_dwordx4 v[130:133], v[130:131], off offset:256
	s_mov_b64 s[16:17], -1
	s_andn2_b64 vcc, exec, s[4:5]
	s_waitcnt vmcnt(7)
	v_lshlrev_b32_e32 v188, 16, v174
	v_and_b32_e32 v189, 0xffff0000, v174
	v_lshlrev_b32_e32 v174, 16, v175
	v_and_b32_e32 v175, 0xffff0000, v175
	v_pk_mul_f32 v[128:129], v[128:129], v[174:175]
	v_lshlrev_b32_e32 v174, 16, v176
	v_and_b32_e32 v175, 0xffff0000, v176
	v_pk_mul_f32 v[126:127], v[126:127], v[188:189]
	v_pk_mul_f32 v[174:175], v[122:123], v[174:175]
	v_lshlrev_b32_e32 v122, 16, v177
	v_and_b32_e32 v123, 0xffff0000, v177
	v_pk_mul_f32 v[176:177], v[124:125], v[122:123]
	v_cvt_pk_bf16_f32 v122, v126, v127
	v_lshl_add_u64 v[126:127], s[6:7], 0, v[186:187]
	v_lshl_add_u64 v[126:127], v[126:127], 0, s[20:21]
	v_cvt_pk_bf16_f32 v123, v128, v129
	v_cvt_pk_bf16_f32 v124, v174, v175
	v_cvt_pk_bf16_f32 v125, v176, v177
	v_lshl_add_u64 v[126:127], v[126:127], 0, v[0:1]
	global_store_dwordx4 v[126:127], v[122:125], off
	s_waitcnt vmcnt(7)
	s_nop 1
	v_lshlrev_b32_e32 v122, 16, v178
	v_and_b32_e32 v123, 0xffff0000, v178
	v_pk_mul_f32 v[114:115], v[114:115], v[122:123]
	v_lshlrev_b32_e32 v122, 16, v179
	v_and_b32_e32 v123, 0xffff0000, v179
	v_pk_mul_f32 v[116:117], v[116:117], v[122:123]
	v_lshlrev_b32_e32 v122, 16, v180
	v_and_b32_e32 v123, 0xffff0000, v180
	v_pk_mul_f32 v[122:123], v[106:107], v[122:123]
	v_lshlrev_b32_e32 v106, 16, v181
	v_and_b32_e32 v107, 0xffff0000, v181
	v_pk_mul_f32 v[124:125], v[108:109], v[106:107]
	v_cvt_pk_bf16_f32 v106, v114, v115
	v_cvt_pk_bf16_f32 v107, v116, v117
	v_cvt_pk_bf16_f32 v108, v122, v123
	v_cvt_pk_bf16_f32 v109, v124, v125
	global_store_dwordx4 v[126:127], v[106:109], off offset:256
	s_waitcnt vmcnt(7)
	v_lshlrev_b32_e32 v114, 16, v184
	v_and_b32_e32 v115, 0xffff0000, v184
	v_lshlrev_b32_e32 v106, 16, v182
	v_and_b32_e32 v107, 0xffff0000, v182
	v_lshlrev_b32_e32 v108, 16, v183
	v_and_b32_e32 v109, 0xffff0000, v183
	v_pk_mul_f32 v[106:107], v[118:119], v[106:107]
	v_pk_mul_f32 v[108:109], v[120:121], v[108:109]
	v_pk_mul_f32 v[110:111], v[110:111], v[114:115]
	v_lshlrev_b32_e32 v114, 16, v185
	v_and_b32_e32 v115, 0xffff0000, v185
	v_cvt_pk_bf16_f32 v106, v106, v107
	v_cvt_pk_bf16_f32 v107, v108, v109
	v_cvt_pk_bf16_f32 v108, v110, v111
	v_lshl_add_u64 v[110:111], s[6:7], 0, v[168:169]
	v_pk_mul_f32 v[112:113], v[112:113], v[114:115]
	v_lshl_add_u64 v[110:111], v[110:111], 0, s[20:21]
	v_cvt_pk_bf16_f32 v109, v112, v113
	v_lshl_add_u64 v[110:111], v[110:111], 0, v[0:1]
	global_store_dwordx4 v[110:111], v[106:109], off
	s_waitcnt vmcnt(7)
	s_nop 1
	v_lshlrev_b32_e32 v106, 16, v146
	v_and_b32_e32 v107, 0xffff0000, v146
	v_pk_mul_f32 v[102:103], v[102:103], v[106:107]
	v_lshlrev_b32_e32 v106, 16, v147
	v_and_b32_e32 v107, 0xffff0000, v147
	v_pk_mul_f32 v[104:105], v[104:105], v[106:107]
	v_lshlrev_b32_e32 v106, 16, v148
	v_and_b32_e32 v107, 0xffff0000, v148
	v_pk_mul_f32 v[106:107], v[94:95], v[106:107]
	v_lshlrev_b32_e32 v94, 16, v149
	v_and_b32_e32 v95, 0xffff0000, v149
	v_pk_mul_f32 v[108:109], v[96:97], v[94:95]
	v_cvt_pk_bf16_f32 v94, v102, v103
	v_cvt_pk_bf16_f32 v95, v104, v105
	v_cvt_pk_bf16_f32 v96, v106, v107
	v_cvt_pk_bf16_f32 v97, v108, v109
	global_store_dwordx4 v[110:111], v[94:97], off offset:256
	s_waitcnt vmcnt(7)
	s_nop 1
	v_lshlrev_b32_e32 v94, 16, v142
	v_and_b32_e32 v95, 0xffff0000, v142
	v_pk_mul_f32 v[94:95], v[98:99], v[94:95]
	v_lshlrev_b32_e32 v98, 16, v144
	v_and_b32_e32 v99, 0xffff0000, v144
	v_lshlrev_b32_e32 v96, 16, v143
	v_and_b32_e32 v97, 0xffff0000, v143
	v_pk_mul_f32 v[98:99], v[90:91], v[98:99]
	v_lshlrev_b32_e32 v90, 16, v145
	v_and_b32_e32 v91, 0xffff0000, v145
	v_pk_mul_f32 v[96:97], v[100:101], v[96:97]
	v_pk_mul_f32 v[100:101], v[92:93], v[90:91]
	v_cvt_pk_bf16_f32 v90, v94, v95
	v_lshl_add_u64 v[94:95], s[6:7], 0, v[166:167]
	v_lshl_add_u64 v[94:95], v[94:95], 0, s[20:21]
	v_cvt_pk_bf16_f32 v91, v96, v97
	v_cvt_pk_bf16_f32 v92, v98, v99
	v_cvt_pk_bf16_f32 v93, v100, v101
	v_lshl_add_u64 v[94:95], v[94:95], 0, v[0:1]
	global_store_dwordx4 v[94:95], v[90:93], off
	s_waitcnt vmcnt(7)
; __device__ __forceinline__ u32x4 pack8(const f32x4 v0, const f32x4 v1) { u32x4 w; w.x = cvt_pk_bf16(v0[0], v0[1]); w.y = cvt_pk_bf16(v0[2], v0[3]); w.z = cvt_pk_bf16(v1[0], v1[1]); w.w = cvt_pk_bf16(v1[2], v1[3]); return w; }
; __device__ __forceinline__ float bf_lo(unsigned w) { return __uint_as_float(w << 16); }
; __device__ __forceinline__ float bf_hi(unsigned w) { return __uint_as_float(w & 0xffff0000u); }
;     __device__ __forceinline__ void operator()(const f32x4 (&acc)[2][2][4][2], const Unit& u, int wr, int wc, int fr, int fq) const {
;         _Pragma("unroll") for (int ai = 0; ai < 2; ++ai) {
;             u32x4 gt[4][2], oo[4][2];
;             _Pragma("unroll") for (int m = 0; m < 4; ++m) _Pragma("unroll") for (int bj = 0; bj < 2; ++bj) { const size_t off = (size_t)EPI_ROW(ai, m) * 1024 + u.pn * BM + EPI_CT(bj);
;                 gt[m][bj] = *(const u32x4*)(G + off); if (ADD) oo[m][bj] = *(const u32x4*)(O + off); }
;             _Pragma("unroll") for (int m = 0; m < 4; ++m) _Pragma("unroll") for (int bj = 0; bj < 2; ++bj) { const size_t off = (size_t)EPI_ROW(ai, m) * 1024 + u.pn * BM + EPI_CT(bj);
;                 f32x4 v0 = acc[ai][bj][m][0], v1 = acc[ai][bj][m][1]; const u32x4 g4 = gt[m][bj];
;                 v0[0] *= bf_lo(g4.x); v0[1] *= bf_hi(g4.x); v0[2] *= bf_lo(g4.y); v0[3] *= bf_hi(g4.y); v1[0] *= bf_lo(g4.z); v1[1] *= bf_hi(g4.z); v1[2] *= bf_lo(g4.w); v1[3] *= bf_hi(g4.w);
;                 if (ADD) { const u32x4 o = oo[m][bj];
;                     v0[0] += bf_lo(o.x); v0[1] += bf_hi(o.x); v0[2] += bf_lo(o.y); v0[3] += bf_hi(o.y); v1[0] += bf_lo(o.z); v1[1] += bf_hi(o.z); v1[2] += bf_lo(o.w); v1[3] += bf_hi(o.w); }
;                 *(u32x4*)(O + off) = pack8(v0, v1); }
	s_nop 1
	v_lshlrev_b32_e32 v90, 16, v134
	v_and_b32_e32 v91, 0xffff0000, v134
	v_pk_mul_f32 v[86:87], v[86:87], v[90:91]
	v_lshlrev_b32_e32 v90, 16, v135
	v_and_b32_e32 v91, 0xffff0000, v135
	v_pk_mul_f32 v[88:89], v[88:89], v[90:91]
	v_lshlrev_b32_e32 v90, 16, v136
	v_and_b32_e32 v91, 0xffff0000, v136
	v_pk_mul_f32 v[90:91], v[78:79], v[90:91]
	v_lshlrev_b32_e32 v78, 16, v137
	v_and_b32_e32 v79, 0xffff0000, v137
	v_pk_mul_f32 v[92:93], v[80:81], v[78:79]
	v_cvt_pk_bf16_f32 v78, v86, v87
	v_cvt_pk_bf16_f32 v79, v88, v89
	v_cvt_pk_bf16_f32 v80, v90, v91
	v_cvt_pk_bf16_f32 v81, v92, v93
	global_store_dwordx4 v[94:95], v[78:81], off offset:256
	s_waitcnt vmcnt(7)
	s_nop 1
	v_lshlrev_b32_e32 v78, 16, v138
	v_and_b32_e32 v79, 0xffff0000, v138
	v_pk_mul_f32 v[78:79], v[82:83], v[78:79]
	v_lshlrev_b32_e32 v82, 16, v140
	v_and_b32_e32 v83, 0xffff0000, v140
	v_lshlrev_b32_e32 v80, 16, v139
	v_and_b32_e32 v81, 0xffff0000, v139
	v_pk_mul_f32 v[82:83], v[74:75], v[82:83]
	v_lshlrev_b32_e32 v74, 16, v141
	v_and_b32_e32 v75, 0xffff0000, v141
	v_pk_mul_f32 v[80:81], v[84:85], v[80:81]
	v_pk_mul_f32 v[84:85], v[76:77], v[74:75]
	v_cvt_pk_bf16_f32 v74, v78, v79
	v_lshl_add_u64 v[78:79], s[6:7], 0, v[164:165]
	v_lshl_add_u64 v[78:79], v[78:79], 0, s[20:21]
	v_cvt_pk_bf16_f32 v75, v80, v81
	v_cvt_pk_bf16_f32 v76, v82, v83
	v_cvt_pk_bf16_f32 v77, v84, v85
	v_lshl_add_u64 v[78:79], v[78:79], 0, v[0:1]
	global_store_dwordx4 v[78:79], v[74:77], off
	s_waitcnt vmcnt(7)
	s_nop 1
	v_lshlrev_b32_e32 v74, 16, v130
	v_and_b32_e32 v75, 0xffff0000, v130
	v_pk_mul_f32 v[70:71], v[70:71], v[74:75]
	v_lshlrev_b32_e32 v74, 16, v131
	v_and_b32_e32 v75, 0xffff0000, v131
	v_pk_mul_f32 v[72:73], v[72:73], v[74:75]
	v_lshlrev_b32_e32 v74, 16, v132
	v_and_b32_e32 v75, 0xffff0000, v132
	v_pk_mul_f32 v[74:75], v[66:67], v[74:75]
	v_lshlrev_b32_e32 v66, 16, v133
	v_and_b32_e32 v67, 0xffff0000, v133
	v_pk_mul_f32 v[76:77], v[68:69], v[66:67]
	v_cvt_pk_bf16_f32 v66, v70, v71
	v_cvt_pk_bf16_f32 v67, v72, v73
	v_cvt_pk_bf16_f32 v68, v74, v75
	v_cvt_pk_bf16_f32 v69, v76, v77
	global_store_dwordx4 v[78:79], v[66:69], off offset:256
	s_nop 1
	v_add_u32_e32 v66, 0x80, v162
	v_ashrrev_i32_e32 v67, 31, v66
	v_lshlrev_b64 v[98:99], 11, v[66:67]
	v_lshl_add_u64 v[66:67], s[22:23], 0, v[98:99]
	v_lshl_add_u64 v[66:67], v[66:67], 0, v[0:1]
	global_load_dwordx4 v[70:73], v[66:67], off
	global_load_dwordx4 v[74:77], v[66:67], off offset:256
	v_add_u32_e32 v66, 0x90, v162
	v_ashrrev_i32_e32 v67, 31, v66
	v_lshlrev_b64 v[100:101], 11, v[66:67]
	v_lshl_add_u64 v[66:67], s[22:23], 0, v[100:101]
	v_lshl_add_u64 v[66:67], v[66:67], 0, v[0:1]
	global_load_dwordx4 v[78:81], v[66:67], off
	global_load_dwordx4 v[82:85], v[66:67], off offset:256
	v_add_u32_e32 v66, 0xa0, v162
	v_ashrrev_i32_e32 v67, 31, v66
	v_lshlrev_b64 v[102:103], 11, v[66:67]
	v_lshl_add_u64 v[66:67], s[22:23], 0, v[102:103]
	v_lshl_add_u64 v[66:67], v[66:67], 0, v[0:1]
	global_load_dwordx4 v[86:89], v[66:67], off
	global_load_dwordx4 v[90:93], v[66:67], off offset:256
	v_add_u32_e32 v66, 0xb0, v162
	v_ashrrev_i32_e32 v67, 31, v66
	v_lshlrev_b64 v[104:105], 11, v[66:67]
	v_lshl_add_u64 v[66:67], s[22:23], 0, v[104:105]
	v_lshl_add_u64 v[66:67], v[66:67], 0, v[0:1]
	global_load_dwordx4 v[94:97], v[66:67], off
	s_nop 0
	global_load_dwordx4 v[66:69], v[66:67], off offset:256
	s_waitcnt vmcnt(7)
	v_lshlrev_b32_e32 v106, 16, v70
	v_and_b32_e32 v107, 0xffff0000, v70
	v_lshlrev_b32_e32 v70, 16, v71
	v_and_b32_e32 v71, 0xffff0000, v71
	v_pk_mul_f32 v[64:65], v[64:65], v[70:71]
	v_lshlrev_b32_e32 v70, 16, v72
	v_and_b32_e32 v71, 0xffff0000, v72
	v_pk_mul_f32 v[62:63], v[62:63], v[106:107]
	v_pk_mul_f32 v[70:71], v[58:59], v[70:71]
	v_lshlrev_b32_e32 v58, 16, v73
	v_and_b32_e32 v59, 0xffff0000, v73
	v_pk_mul_f32 v[72:73], v[60:61], v[58:59]
	v_cvt_pk_bf16_f32 v58, v62, v63
	v_lshl_add_u64 v[62:63], s[6:7], 0, v[98:99]
	v_lshl_add_u64 v[62:63], v[62:63], 0, s[20:21]
	v_cvt_pk_bf16_f32 v59, v64, v65
	v_cvt_pk_bf16_f32 v60, v70, v71
	v_cvt_pk_bf16_f32 v61, v72, v73
	v_lshl_add_u64 v[62:63], v[62:63], 0, v[0:1]
	global_store_dwordx4 v[62:63], v[58:61], off
	s_waitcnt vmcnt(7)
	s_nop 0
	v_lshlrev_b32_e32 v58, 16, v74
	v_and_b32_e32 v59, 0xffff0000, v74
	v_pk_mul_f32 v[54:55], v[54:55], v[58:59]
	v_lshlrev_b32_e32 v58, 16, v75
	v_and_b32_e32 v59, 0xffff0000, v75
	v_pk_mul_f32 v[56:57], v[56:57], v[58:59]
	v_lshlrev_b32_e32 v58, 16, v76
	v_and_b32_e32 v59, 0xffff0000, v76
	v_pk_mul_f32 v[58:59], v[46:47], v[58:59]
	v_lshlrev_b32_e32 v46, 16, v77
	v_and_b32_e32 v47, 0xffff0000, v77
	v_pk_mul_f32 v[60:61], v[48:49], v[46:47]
	v_cvt_pk_bf16_f32 v46, v54, v55
	v_cvt_pk_bf16_f32 v47, v56, v57
	v_cvt_pk_bf16_f32 v48, v58, v59
	v_cvt_pk_bf16_f32 v49, v60, v61
	global_store_dwordx4 v[62:63], v[46:49], off offset:256
	s_waitcnt vmcnt(7)
; __device__ __forceinline__ u32x4 pack8(const f32x4 v0, const f32x4 v1) { u32x4 w; w.x = cvt_pk_bf16(v0[0], v0[1]); w.y = cvt_pk_bf16(v0[2], v0[3]); w.z = cvt_pk_bf16(v1[0], v1[1]); w.w = cvt_pk_bf16(v1[2], v1[3]); return w; }
; __device__ __forceinline__ float bf_lo(unsigned w) { return __uint_as_float(w << 16); }
; __device__ __forceinline__ float bf_hi(unsigned w) { return __uint_as_float(w & 0xffff0000u); }
;     __device__ __forceinline__ void operator()(const f32x4 (&acc)[2][2][4][2], const Unit& u, int wr, int wc, int fr, int fq) const {
;         _Pragma("unroll") for (int ai = 0; ai < 2; ++ai) {
;             u32x4 gt[4][2], oo[4][2];
;             _Pragma("unroll") for (int m = 0; m < 4; ++m) _Pragma("unroll") for (int bj = 0; bj < 2; ++bj) { const size_t off = (size_t)EPI_ROW(ai, m) * 1024 + u.pn * BM + EPI_CT(bj);
;                 gt[m][bj] = *(const u32x4*)(G + off); if (ADD) oo[m][bj] = *(const u32x4*)(O + off); }
;             _Pragma("unroll") for (int m = 0; m < 4; ++m) _Pragma("unroll") for (int bj = 0; bj < 2; ++bj) { const size_t off = (size_t)EPI_ROW(ai, m) * 1024 + u.pn * BM + EPI_CT(bj);
;                 f32x4 v0 = acc[ai][bj][m][0], v1 = acc[ai][bj][m][1]; const u32x4 g4 = gt[m][bj];
;                 v0[0] *= bf_lo(g4.x); v0[1] *= bf_hi(g4.x); v0[2] *= bf_lo(g4.y); v0[3] *= bf_hi(g4.y); v1[0] *= bf_lo(g4.z); v1[1] *= bf_hi(g4.z); v1[2] *= bf_lo(g4.w); v1[3] *= bf_hi(g4.w);
;                 if (ADD) { const u32x4 o = oo[m][bj];
;                     v0[0] += bf_lo(o.x); v0[1] += bf_hi(o.x); v0[2] += bf_lo(o.y); v0[3] += bf_hi(o.y); v1[0] += bf_lo(o.z); v1[1] += bf_hi(o.z); v1[2] += bf_lo(o.w); v1[3] += bf_hi(o.w); }
;                 *(u32x4*)(O + off) = pack8(v0, v1); }
	s_nop 0
	v_lshlrev_b32_e32 v46, 16, v78
	v_and_b32_e32 v47, 0xffff0000, v78
	v_pk_mul_f32 v[46:47], v[50:51], v[46:47]
	v_lshlrev_b32_e32 v50, 16, v80
	v_and_b32_e32 v51, 0xffff0000, v80
	v_lshlrev_b32_e32 v48, 16, v79
	v_and_b32_e32 v49, 0xffff0000, v79
	v_pk_mul_f32 v[50:51], v[42:43], v[50:51]
	v_lshlrev_b32_e32 v42, 16, v81
	v_and_b32_e32 v43, 0xffff0000, v81
	v_pk_mul_f32 v[48:49], v[52:53], v[48:49]
	v_pk_mul_f32 v[52:53], v[44:45], v[42:43]
	v_cvt_pk_bf16_f32 v42, v46, v47
	v_lshl_add_u64 v[46:47], s[6:7], 0, v[100:101]
	v_lshl_add_u64 v[46:47], v[46:47], 0, s[20:21]
	v_cvt_pk_bf16_f32 v43, v48, v49
	v_cvt_pk_bf16_f32 v44, v50, v51
	v_cvt_pk_bf16_f32 v45, v52, v53
	v_lshl_add_u64 v[46:47], v[46:47], 0, v[0:1]
	global_store_dwordx4 v[46:47], v[42:45], off
	s_waitcnt vmcnt(7)
	s_nop 0
	v_lshlrev_b32_e32 v42, 16, v82
	v_and_b32_e32 v43, 0xffff0000, v82
	v_pk_mul_f32 v[38:39], v[38:39], v[42:43]
	v_lshlrev_b32_e32 v42, 16, v83
	v_and_b32_e32 v43, 0xffff0000, v83
	v_pk_mul_f32 v[40:41], v[40:41], v[42:43]
	v_lshlrev_b32_e32 v42, 16, v84
	v_and_b32_e32 v43, 0xffff0000, v84
	v_pk_mul_f32 v[42:43], v[30:31], v[42:43]
	v_lshlrev_b32_e32 v30, 16, v85
	v_and_b32_e32 v31, 0xffff0000, v85
	v_pk_mul_f32 v[44:45], v[32:33], v[30:31]
	v_cvt_pk_bf16_f32 v30, v38, v39
	v_cvt_pk_bf16_f32 v31, v40, v41
	v_cvt_pk_bf16_f32 v32, v42, v43
	v_cvt_pk_bf16_f32 v33, v44, v45
	global_store_dwordx4 v[46:47], v[30:33], off offset:256
	s_waitcnt vmcnt(7)
	s_nop 0
	v_lshlrev_b32_e32 v30, 16, v86
	v_and_b32_e32 v31, 0xffff0000, v86
	v_pk_mul_f32 v[30:31], v[34:35], v[30:31]
	v_lshlrev_b32_e32 v34, 16, v88
	v_and_b32_e32 v35, 0xffff0000, v88
	v_lshlrev_b32_e32 v32, 16, v87
	v_and_b32_e32 v33, 0xffff0000, v87
	v_pk_mul_f32 v[34:35], v[26:27], v[34:35]
	v_lshlrev_b32_e32 v26, 16, v89
	v_and_b32_e32 v27, 0xffff0000, v89
	v_pk_mul_f32 v[32:33], v[36:37], v[32:33]
	v_pk_mul_f32 v[36:37], v[28:29], v[26:27]
	v_cvt_pk_bf16_f32 v26, v30, v31
	v_lshl_add_u64 v[30:31], s[6:7], 0, v[102:103]
	v_lshl_add_u64 v[30:31], v[30:31], 0, s[20:21]
	v_cvt_pk_bf16_f32 v27, v32, v33
	v_cvt_pk_bf16_f32 v28, v34, v35
	v_cvt_pk_bf16_f32 v29, v36, v37
	v_lshl_add_u64 v[30:31], v[30:31], 0, v[0:1]
	global_store_dwordx4 v[30:31], v[26:29], off
	s_waitcnt vmcnt(7)
	s_nop 0
	v_lshlrev_b32_e32 v26, 16, v90
	v_and_b32_e32 v27, 0xffff0000, v90
	v_pk_mul_f32 v[22:23], v[22:23], v[26:27]
	v_lshlrev_b32_e32 v26, 16, v91
	v_and_b32_e32 v27, 0xffff0000, v91
	v_pk_mul_f32 v[24:25], v[24:25], v[26:27]
	v_lshlrev_b32_e32 v26, 16, v92
	v_and_b32_e32 v27, 0xffff0000, v92
	v_pk_mul_f32 v[26:27], v[14:15], v[26:27]
	v_lshlrev_b32_e32 v14, 16, v93
	v_and_b32_e32 v15, 0xffff0000, v93
	v_pk_mul_f32 v[28:29], v[16:17], v[14:15]
	v_cvt_pk_bf16_f32 v14, v22, v23
	v_cvt_pk_bf16_f32 v15, v24, v25
	v_cvt_pk_bf16_f32 v16, v26, v27
	v_cvt_pk_bf16_f32 v17, v28, v29
	global_store_dwordx4 v[30:31], v[14:17], off offset:256
	s_waitcnt vmcnt(7)
	s_nop 0
	v_lshlrev_b32_e32 v14, 16, v94
	v_and_b32_e32 v15, 0xffff0000, v94
	v_pk_mul_f32 v[14:15], v[18:19], v[14:15]
	v_lshlrev_b32_e32 v18, 16, v96
	v_and_b32_e32 v19, 0xffff0000, v96
	v_lshlrev_b32_e32 v16, 16, v95
	v_and_b32_e32 v17, 0xffff0000, v95
	v_pk_mul_f32 v[18:19], v[10:11], v[18:19]
	v_lshlrev_b32_e32 v10, 16, v97
	v_and_b32_e32 v11, 0xffff0000, v97
	v_pk_mul_f32 v[16:17], v[20:21], v[16:17]
	v_pk_mul_f32 v[20:21], v[12:13], v[10:11]
	v_cvt_pk_bf16_f32 v10, v14, v15
	v_lshl_add_u64 v[14:15], s[6:7], 0, v[104:105]
	v_lshl_add_u64 v[14:15], v[14:15], 0, s[20:21]
	v_cvt_pk_bf16_f32 v11, v16, v17
	v_cvt_pk_bf16_f32 v12, v18, v19
	v_cvt_pk_bf16_f32 v13, v20, v21
	v_lshl_add_u64 v[14:15], v[14:15], 0, v[0:1]
	global_store_dwordx4 v[14:15], v[10:13], off
	s_waitcnt vmcnt(7)
	s_nop 0
	v_lshlrev_b32_e32 v10, 16, v66
	v_and_b32_e32 v11, 0xffff0000, v66
	v_pk_mul_f32 v[6:7], v[6:7], v[10:11]
	v_lshlrev_b32_e32 v10, 16, v67
	v_and_b32_e32 v11, 0xffff0000, v67
	v_pk_mul_f32 v[8:9], v[8:9], v[10:11]
	v_lshlrev_b32_e32 v10, 16, v68
	v_and_b32_e32 v11, 0xffff0000, v68
	v_pk_mul_f32 v[10:11], v[2:3], v[10:11]
	v_lshlrev_b32_e32 v2, 16, v69
	v_and_b32_e32 v3, 0xffff0000, v69
	v_pk_mul_f32 v[12:13], v[4:5], v[2:3]
	v_cvt_pk_bf16_f32 v2, v6, v7
	v_cvt_pk_bf16_f32 v3, v8, v9
	v_cvt_pk_bf16_f32 v4, v10, v11
	v_cvt_pk_bf16_f32 v5, v12, v13
	global_store_dwordx4 v[14:15], v[2:5], off offset:256
	s_cbranch_vccnz .LBB0_559
	s_andn2_b64 vcc, exec, s[0:1]
	s_cbranch_vccnz .LBB0_558
	s_branch .LBB0_558

; __device__ __forceinline__ u32x4 pack8(const f32x4 v0, const f32x4 v1) { u32x4 w; w.x = cvt_pk_bf16(v0[0], v0[1]); w.y = cvt_pk_bf16(v0[2], v0[3]); w.z = cvt_pk_bf16(v1[0], v1[1]); w.w = cvt_pk_bf16(v1[2], v1[3]); return w; }
; __device__ __forceinline__ float bf_lo(unsigned w) { return __uint_as_float(w << 16); }
; __device__ __forceinline__ float bf_hi(unsigned w) { return __uint_as_float(w & 0xffff0000u); }
;     __device__ __forceinline__ void operator()(const f32x4 (&acc)[2][2][4][2], const Unit& u, int wr, int wc, int fr, int fq) const {
;         _Pragma("unroll") for (int ai = 0; ai < 2; ++ai) {
;             u32x4 gt[4][2], oo[4][2];
;             _Pragma("unroll") for (int m = 0; m < 4; ++m) _Pragma("unroll") for (int bj = 0; bj < 2; ++bj) { const size_t off = (size_t)EPI_ROW(ai, m) * 1024 + u.pn * BM + EPI_CT(bj);
;                 gt[m][bj] = *(const u32x4*)(G + off); if (ADD) oo[m][bj] = *(const u32x4*)(O + off); }
;             _Pragma("unroll") for (int m = 0; m < 4; ++m) _Pragma("unroll") for (int bj = 0; bj < 2; ++bj) { const size_t off = (size_t)EPI_ROW(ai, m) * 1024 + u.pn * BM + EPI_CT(bj);
;                 f32x4 v0 = acc[ai][bj][m][0], v1 = acc[ai][bj][m][1]; const u32x4 g4 = gt[m][bj];
;                 v0[0] *= bf_lo(g4.x); v0[1] *= bf_hi(g4.x); v0[2] *= bf_lo(g4.y); v0[3] *= bf_hi(g4.y); v1[0] *= bf_lo(g4.z); v1[1] *= bf_hi(g4.z); v1[2] *= bf_lo(g4.w); v1[3] *= bf_hi(g4.w);
;                 if (ADD) { const u32x4 o = oo[m][bj];
;                     v0[0] += bf_lo(o.x); v0[1] += bf_hi(o.x); v0[2] += bf_lo(o.y); v0[3] += bf_hi(o.y); v1[0] += bf_lo(o.z); v1[1] += bf_hi(o.z); v1[2] += bf_lo(o.w); v1[3] += bf_hi(o.w); }
;                 *(u32x4*)(O + off) = pack8(v0, v1); }
.LBB0_635:
	v_lshl_add_u32 v210, s46, 8, v203
	s_lshl_b32 s22, s33, 8
	v_ashrrev_i32_e32 v211, 31, v210
	s_ashr_i32 s23, s22, 31
	v_lshlrev_b64 v[130:131], 10, v[210:211]
	v_lshl_add_u64 v[130:131], v[130:131], 0, s[22:23]
	v_or_b32_e32 v132, v130, v202
	v_mov_b32_e32 v133, v131
	v_lshlrev_b64 v[132:133], 1, v[132:133]
	v_lshl_add_u64 v[134:135], s[6:7], 0, v[132:133]
	v_lshl_add_u64 v[132:133], s[8:9], 0, v[132:133]
	global_load_dwordx4 v[190:193], v[134:135], off
	global_load_dwordx4 v[186:189], v[132:133], off
	v_or_b32_e32 v130, v130, v204
	v_lshlrev_b64 v[130:131], 1, v[130:131]
	v_lshl_add_u64 v[132:133], s[6:7], 0, v[130:131]
	v_lshl_add_u64 v[130:131], s[8:9], 0, v[130:131]
	v_or_b32_e32 v224, 16, v210
	global_load_dwordx4 v[182:185], v[132:133], off
	global_load_dwordx4 v[178:181], v[130:131], off
	v_ashrrev_i32_e32 v225, 31, v224
	v_lshlrev_b64 v[130:131], 10, v[224:225]
	v_lshl_add_u64 v[130:131], v[130:131], 0, s[22:23]
	v_or_b32_e32 v132, v130, v202
	v_mov_b32_e32 v133, v131
	v_lshlrev_b64 v[132:133], 1, v[132:133]
	v_lshl_add_u64 v[134:135], s[6:7], 0, v[132:133]
	v_lshl_add_u64 v[132:133], s[8:9], 0, v[132:133]
	global_load_dwordx4 v[166:169], v[134:135], off
	global_load_dwordx4 v[162:165], v[132:133], off
	v_or_b32_e32 v130, v130, v204
	v_lshlrev_b64 v[130:131], 1, v[130:131]
	v_lshl_add_u64 v[132:133], s[6:7], 0, v[130:131]
	v_lshl_add_u64 v[130:131], s[8:9], 0, v[130:131]
	v_or_b32_e32 v222, 32, v210
	global_load_dwordx4 v[142:145], v[132:133], off
	global_load_dwordx4 v[138:141], v[130:131], off
	v_ashrrev_i32_e32 v223, 31, v222
	v_lshlrev_b64 v[130:131], 10, v[222:223]
	v_lshl_add_u64 v[130:131], v[130:131], 0, s[22:23]
	v_or_b32_e32 v132, v130, v202
	v_mov_b32_e32 v133, v131
	v_lshlrev_b64 v[132:133], 1, v[132:133]
	v_lshl_add_u64 v[134:135], s[6:7], 0, v[132:133]
	v_lshl_add_u64 v[132:133], s[8:9], 0, v[132:133]
	global_load_dwordx4 v[158:161], v[134:135], off
	global_load_dwordx4 v[154:157], v[132:133], off
	v_or_b32_e32 v220, 48, v210
	v_ashrrev_i32_e32 v221, 31, v220
	v_lshlrev_b64 v[146:147], 10, v[220:221]
	v_lshl_add_u64 v[146:147], v[146:147], 0, s[22:23]
	v_or_b32_e32 v130, v130, v204
	v_or_b32_e32 v148, v146, v202
	v_mov_b32_e32 v149, v147
	v_lshlrev_b64 v[130:131], 1, v[130:131]
	v_lshlrev_b64 v[148:149], 1, v[148:149]
	v_lshl_add_u64 v[132:133], s[6:7], 0, v[130:131]
	v_lshl_add_u64 v[130:131], s[8:9], 0, v[130:131]
	v_lshl_add_u64 v[150:151], s[6:7], 0, v[148:149]
	v_lshl_add_u64 v[148:149], s[8:9], 0, v[148:149]
	global_load_dwordx4 v[134:137], v[132:133], off
	global_load_dwordx4 v[170:173], v[148:149], off
	global_load_dwordx4 v[174:177], v[150:151], off
	v_or_b32_e32 v146, v146, v204
	global_load_dwordx4 v[130:133], v[130:131], off
	v_lshlrev_b64 v[146:147], 1, v[146:147]
	v_lshl_add_u64 v[148:149], s[6:7], 0, v[146:147]
	v_lshl_add_u64 v[146:147], s[8:9], 0, v[146:147]
	global_load_dwordx4 v[150:153], v[148:149], off
	v_lshlrev_b64 v[212:213], 11, v[210:211]
	global_load_dwordx4 v[146:149], v[146:147], off
	s_lshl_b64 s[24:25], s[22:23], 1
	v_lshlrev_b32_e32 v0, 1, v202
	s_mov_b64 s[16:17], -1
	s_andn2_b64 vcc, exec, s[4:5]
	s_waitcnt vmcnt(14)
	v_lshlrev_b32_e32 v214, 16, v190
	v_and_b32_e32 v215, 0xffff0000, v190
	v_lshlrev_b32_e32 v216, 16, v186
	v_and_b32_e32 v217, 0xffff0000, v186
	v_lshlrev_b32_e32 v190, 16, v191
	v_and_b32_e32 v191, 0xffff0000, v191
	v_lshlrev_b32_e32 v186, 16, v187
	v_and_b32_e32 v187, 0xffff0000, v187
	v_pk_fma_f32 v[128:129], v[128:129], v[190:191], v[186:187]
	v_lshlrev_b32_e32 v186, 16, v192
	v_and_b32_e32 v187, 0xffff0000, v192
	v_lshlrev_b32_e32 v190, 16, v188
	v_and_b32_e32 v191, 0xffff0000, v188
	v_pk_fma_f32 v[126:127], v[126:127], v[214:215], v[216:217]
	v_pk_fma_f32 v[186:187], v[122:123], v[186:187], v[190:191]
	v_lshlrev_b32_e32 v122, 16, v193
	v_and_b32_e32 v123, 0xffff0000, v193
	v_lshlrev_b32_e32 v188, 16, v189
	v_and_b32_e32 v189, 0xffff0000, v189
	v_pk_fma_f32 v[188:189], v[124:125], v[122:123], v[188:189]
	v_cvt_pk_bf16_f32 v122, v126, v127
	v_lshl_add_u64 v[126:127], s[8:9], 0, v[212:213]
	v_lshl_add_u64 v[126:127], v[126:127], 0, s[24:25]
	v_cvt_pk_bf16_f32 v123, v128, v129
	v_cvt_pk_bf16_f32 v124, v186, v187
	v_cvt_pk_bf16_f32 v125, v188, v189
	v_lshl_add_u64 v[126:127], v[126:127], 0, v[0:1]
	global_store_dwordx4 v[126:127], v[122:125], off
	s_waitcnt vmcnt(13)
	s_nop 1
	v_lshlrev_b32_e32 v122, 16, v182
	v_and_b32_e32 v123, 0xffff0000, v182
	v_lshlrev_b32_e32 v124, 16, v178
	v_and_b32_e32 v125, 0xffff0000, v178
	v_pk_fma_f32 v[118:119], v[118:119], v[122:123], v[124:125]
	v_lshlrev_b32_e32 v122, 16, v183
	v_and_b32_e32 v123, 0xffff0000, v183
	v_lshlrev_b32_e32 v124, 16, v179
	v_and_b32_e32 v125, 0xffff0000, v179
	v_pk_fma_f32 v[120:121], v[120:121], v[122:123], v[124:125]
	v_lshlrev_b32_e32 v122, 16, v184
	v_and_b32_e32 v123, 0xffff0000, v184
	v_lshlrev_b32_e32 v124, 16, v180
	v_and_b32_e32 v125, 0xffff0000, v180
	v_pk_fma_f32 v[122:123], v[114:115], v[122:123], v[124:125]
	v_lshlrev_b32_e32 v114, 16, v185
	v_and_b32_e32 v115, 0xffff0000, v185
	v_lshlrev_b32_e32 v124, 16, v181
	v_and_b32_e32 v125, 0xffff0000, v181
	v_pk_fma_f32 v[124:125], v[116:117], v[114:115], v[124:125]
	v_cvt_pk_bf16_f32 v114, v118, v119
	v_cvt_pk_bf16_f32 v115, v120, v121
	v_cvt_pk_bf16_f32 v116, v122, v123
	v_cvt_pk_bf16_f32 v117, v124, v125
	global_store_dwordx4 v[126:127], v[114:117], off offset:256
	s_waitcnt vmcnt(12)
; __device__ __forceinline__ u32x4 pack8(const f32x4 v0, const f32x4 v1) { u32x4 w; w.x = cvt_pk_bf16(v0[0], v0[1]); w.y = cvt_pk_bf16(v0[2], v0[3]); w.z = cvt_pk_bf16(v1[0], v1[1]); w.w = cvt_pk_bf16(v1[2], v1[3]); return w; }
; __device__ __forceinline__ float bf_lo(unsigned w) { return __uint_as_float(w << 16); }
; __device__ __forceinline__ float bf_hi(unsigned w) { return __uint_as_float(w & 0xffff0000u); }
;     __device__ __forceinline__ void operator()(const f32x4 (&acc)[2][2][4][2], const Unit& u, int wr, int wc, int fr, int fq) const {
;         _Pragma("unroll") for (int ai = 0; ai < 2; ++ai) {
;             u32x4 gt[4][2], oo[4][2];
;             _Pragma("unroll") for (int m = 0; m < 4; ++m) _Pragma("unroll") for (int bj = 0; bj < 2; ++bj) { const size_t off = (size_t)EPI_ROW(ai, m) * 1024 + u.pn * BM + EPI_CT(bj);
;                 gt[m][bj] = *(const u32x4*)(G + off); if (ADD) oo[m][bj] = *(const u32x4*)(O + off); }
;             _Pragma("unroll") for (int m = 0; m < 4; ++m) _Pragma("unroll") for (int bj = 0; bj < 2; ++bj) { const size_t off = (size_t)EPI_ROW(ai, m) * 1024 + u.pn * BM + EPI_CT(bj);
;                 f32x4 v0 = acc[ai][bj][m][0], v1 = acc[ai][bj][m][1]; const u32x4 g4 = gt[m][bj];
;                 v0[0] *= bf_lo(g4.x); v0[1] *= bf_hi(g4.x); v0[2] *= bf_lo(g4.y); v0[3] *= bf_hi(g4.y); v1[0] *= bf_lo(g4.z); v1[1] *= bf_hi(g4.z); v1[2] *= bf_lo(g4.w); v1[3] *= bf_hi(g4.w);
;                 if (ADD) { const u32x4 o = oo[m][bj];
;                     v0[0] += bf_lo(o.x); v0[1] += bf_hi(o.x); v0[2] += bf_lo(o.y); v0[3] += bf_hi(o.y); v1[0] += bf_lo(o.z); v1[1] += bf_hi(o.z); v1[2] += bf_lo(o.w); v1[3] += bf_hi(o.w); }
;                 *(u32x4*)(O + off) = pack8(v0, v1); }
	v_lshlrev_b32_e32 v118, 16, v162
	v_and_b32_e32 v119, 0xffff0000, v162
	v_lshlrev_b32_e32 v116, 16, v166
	v_and_b32_e32 v117, 0xffff0000, v166
	v_pk_fma_f32 v[110:111], v[110:111], v[116:117], v[118:119]
	v_lshlrev_b32_e32 v116, 16, v167
	v_and_b32_e32 v117, 0xffff0000, v167
	v_lshlrev_b32_e32 v118, 16, v163
	v_and_b32_e32 v119, 0xffff0000, v163
	v_pk_fma_f32 v[112:113], v[112:113], v[116:117], v[118:119]
	v_lshlrev_b32_e32 v116, 16, v168
	v_and_b32_e32 v117, 0xffff0000, v168
	v_lshlrev_b32_e32 v118, 16, v164
	v_and_b32_e32 v119, 0xffff0000, v164
	v_lshlrev_b64 v[114:115], 11, v[224:225]
	v_pk_fma_f32 v[116:117], v[106:107], v[116:117], v[118:119]
	v_lshlrev_b32_e32 v106, 16, v169
	v_and_b32_e32 v107, 0xffff0000, v169
	v_lshlrev_b32_e32 v118, 16, v165
	v_and_b32_e32 v119, 0xffff0000, v165
	v_pk_fma_f32 v[118:119], v[108:109], v[106:107], v[118:119]
	v_cvt_pk_bf16_f32 v106, v110, v111
	v_lshl_add_u64 v[110:111], s[8:9], 0, v[114:115]
	v_lshl_add_u64 v[110:111], v[110:111], 0, s[24:25]
	v_cvt_pk_bf16_f32 v107, v112, v113
	v_cvt_pk_bf16_f32 v108, v116, v117
	v_cvt_pk_bf16_f32 v109, v118, v119
	v_lshl_add_u64 v[110:111], v[110:111], 0, v[0:1]
	global_store_dwordx4 v[110:111], v[106:109], off
	s_waitcnt vmcnt(11)
	s_nop 1
	v_lshlrev_b32_e32 v106, 16, v142
	v_and_b32_e32 v107, 0xffff0000, v142
	v_lshlrev_b32_e32 v108, 16, v138
	v_and_b32_e32 v109, 0xffff0000, v138
	v_pk_fma_f32 v[102:103], v[102:103], v[106:107], v[108:109]
	v_lshlrev_b32_e32 v106, 16, v143
	v_and_b32_e32 v107, 0xffff0000, v143
	v_lshlrev_b32_e32 v108, 16, v139
	v_and_b32_e32 v109, 0xffff0000, v139
	v_pk_fma_f32 v[104:105], v[104:105], v[106:107], v[108:109]
	v_lshlrev_b32_e32 v106, 16, v144
	v_and_b32_e32 v107, 0xffff0000, v144
	v_lshlrev_b32_e32 v108, 16, v140
	v_and_b32_e32 v109, 0xffff0000, v140
	v_pk_fma_f32 v[106:107], v[98:99], v[106:107], v[108:109]
	v_lshlrev_b32_e32 v98, 16, v145
	v_and_b32_e32 v99, 0xffff0000, v145
	v_lshlrev_b32_e32 v108, 16, v141
	v_and_b32_e32 v109, 0xffff0000, v141
	v_pk_fma_f32 v[108:109], v[100:101], v[98:99], v[108:109]
	v_cvt_pk_bf16_f32 v98, v102, v103
	v_cvt_pk_bf16_f32 v99, v104, v105
	v_cvt_pk_bf16_f32 v100, v106, v107
	v_cvt_pk_bf16_f32 v101, v108, v109
	global_store_dwordx4 v[110:111], v[98:101], off offset:256
	s_waitcnt vmcnt(10)
	v_lshlrev_b32_e32 v102, 16, v154
	v_and_b32_e32 v103, 0xffff0000, v154
	v_lshlrev_b32_e32 v100, 16, v158
	v_and_b32_e32 v101, 0xffff0000, v158
	v_pk_fma_f32 v[94:95], v[94:95], v[100:101], v[102:103]
	v_lshlrev_b32_e32 v100, 16, v159
	v_and_b32_e32 v101, 0xffff0000, v159
	v_lshlrev_b32_e32 v102, 16, v155
	v_and_b32_e32 v103, 0xffff0000, v155
	v_pk_fma_f32 v[96:97], v[96:97], v[100:101], v[102:103]
	v_lshlrev_b32_e32 v100, 16, v160
	v_and_b32_e32 v101, 0xffff0000, v160
	v_lshlrev_b32_e32 v102, 16, v156
	v_and_b32_e32 v103, 0xffff0000, v156
	v_lshlrev_b64 v[98:99], 11, v[222:223]
	v_pk_fma_f32 v[100:101], v[90:91], v[100:101], v[102:103]
	v_lshlrev_b32_e32 v90, 16, v161
	v_and_b32_e32 v91, 0xffff0000, v161
	v_lshlrev_b32_e32 v102, 16, v157
	v_and_b32_e32 v103, 0xffff0000, v157
	v_pk_fma_f32 v[102:103], v[92:93], v[90:91], v[102:103]
	v_cvt_pk_bf16_f32 v90, v94, v95
	v_lshl_add_u64 v[94:95], s[8:9], 0, v[98:99]
	v_lshl_add_u64 v[94:95], v[94:95], 0, s[24:25]
	v_cvt_pk_bf16_f32 v91, v96, v97
	v_cvt_pk_bf16_f32 v92, v100, v101
	v_cvt_pk_bf16_f32 v93, v102, v103
	v_lshl_add_u64 v[94:95], v[94:95], 0, v[0:1]
	global_store_dwordx4 v[94:95], v[90:93], off
	s_waitcnt vmcnt(7)
	v_add_u32_e32 v108, 0xa0, v210
	v_ashrrev_i32_e32 v109, 31, v108
	v_lshlrev_b32_e32 v90, 16, v134
	v_and_b32_e32 v91, 0xffff0000, v134
	v_lshlrev_b32_e32 v92, 16, v130
	v_and_b32_e32 v93, 0xffff0000, v130
	v_pk_fma_f32 v[86:87], v[86:87], v[90:91], v[92:93]
	v_lshlrev_b32_e32 v90, 16, v135
	v_and_b32_e32 v91, 0xffff0000, v135
	v_lshlrev_b32_e32 v92, 16, v131
	v_and_b32_e32 v93, 0xffff0000, v131
	v_pk_fma_f32 v[88:89], v[88:89], v[90:91], v[92:93]
	v_lshlrev_b32_e32 v90, 16, v136
	v_and_b32_e32 v91, 0xffff0000, v136
	v_lshlrev_b32_e32 v92, 16, v132
	v_and_b32_e32 v93, 0xffff0000, v132
	v_pk_fma_f32 v[90:91], v[82:83], v[90:91], v[92:93]
	v_lshlrev_b32_e32 v82, 16, v137
	v_and_b32_e32 v83, 0xffff0000, v137
	v_lshlrev_b32_e32 v92, 16, v133
	v_and_b32_e32 v93, 0xffff0000, v133
	v_pk_fma_f32 v[92:93], v[84:85], v[82:83], v[92:93]
	v_cvt_pk_bf16_f32 v82, v86, v87
	v_cvt_pk_bf16_f32 v83, v88, v89
	v_cvt_pk_bf16_f32 v84, v90, v91
	v_cvt_pk_bf16_f32 v85, v92, v93
	global_store_dwordx4 v[94:95], v[82:85], off offset:256
	s_waitcnt vmcnt(8)
	v_lshlrev_b32_e32 v86, 16, v170
	v_and_b32_e32 v87, 0xffff0000, v170
	v_lshlrev_b32_e32 v84, 16, v174
	v_and_b32_e32 v85, 0xffff0000, v174
	v_pk_fma_f32 v[78:79], v[78:79], v[84:85], v[86:87]
	v_lshlrev_b32_e32 v84, 16, v175
	v_and_b32_e32 v85, 0xffff0000, v175
	v_lshlrev_b32_e32 v86, 16, v171
	v_and_b32_e32 v87, 0xffff0000, v171
	v_pk_fma_f32 v[80:81], v[80:81], v[84:85], v[86:87]
	v_lshlrev_b32_e32 v84, 16, v176
	v_and_b32_e32 v85, 0xffff0000, v176
	v_lshlrev_b32_e32 v86, 16, v172
	v_and_b32_e32 v87, 0xffff0000, v172
	v_lshlrev_b64 v[82:83], 11, v[220:221]
	v_pk_fma_f32 v[84:85], v[74:75], v[84:85], v[86:87]
	v_lshlrev_b32_e32 v74, 16, v177
	v_and_b32_e32 v75, 0xffff0000, v177
	v_lshlrev_b32_e32 v86, 16, v173
	v_and_b32_e32 v87, 0xffff0000, v173
	v_pk_fma_f32 v[86:87], v[76:77], v[74:75], v[86:87]
	v_cvt_pk_bf16_f32 v74, v78, v79
	v_lshl_add_u64 v[78:79], s[8:9], 0, v[82:83]
	v_lshl_add_u64 v[78:79], v[78:79], 0, s[24:25]
	v_cvt_pk_bf16_f32 v75, v80, v81
	v_cvt_pk_bf16_f32 v76, v84, v85
	v_cvt_pk_bf16_f32 v77, v86, v87
	v_lshl_add_u64 v[78:79], v[78:79], 0, v[0:1]
	global_store_dwordx4 v[78:79], v[74:77], off
	s_waitcnt vmcnt(7)
; __device__ __forceinline__ u32x4 pack8(const f32x4 v0, const f32x4 v1) { u32x4 w; w.x = cvt_pk_bf16(v0[0], v0[1]); w.y = cvt_pk_bf16(v0[2], v0[3]); w.z = cvt_pk_bf16(v1[0], v1[1]); w.w = cvt_pk_bf16(v1[2], v1[3]); return w; }
; __device__ __forceinline__ float bf_lo(unsigned w) { return __uint_as_float(w << 16); }
; __device__ __forceinline__ float bf_hi(unsigned w) { return __uint_as_float(w & 0xffff0000u); }
;     __device__ __forceinline__ void operator()(const f32x4 (&acc)[2][2][4][2], const Unit& u, int wr, int wc, int fr, int fq) const {
;         _Pragma("unroll") for (int ai = 0; ai < 2; ++ai) {
;             u32x4 gt[4][2], oo[4][2];
;             _Pragma("unroll") for (int m = 0; m < 4; ++m) _Pragma("unroll") for (int bj = 0; bj < 2; ++bj) { const size_t off = (size_t)EPI_ROW(ai, m) * 1024 + u.pn * BM + EPI_CT(bj);
;                 gt[m][bj] = *(const u32x4*)(G + off); if (ADD) oo[m][bj] = *(const u32x4*)(O + off); }
;             _Pragma("unroll") for (int m = 0; m < 4; ++m) _Pragma("unroll") for (int bj = 0; bj < 2; ++bj) { const size_t off = (size_t)EPI_ROW(ai, m) * 1024 + u.pn * BM + EPI_CT(bj);
;                 f32x4 v0 = acc[ai][bj][m][0], v1 = acc[ai][bj][m][1]; const u32x4 g4 = gt[m][bj];
;                 v0[0] *= bf_lo(g4.x); v0[1] *= bf_hi(g4.x); v0[2] *= bf_lo(g4.y); v0[3] *= bf_hi(g4.y); v1[0] *= bf_lo(g4.z); v1[1] *= bf_hi(g4.z); v1[2] *= bf_lo(g4.w); v1[3] *= bf_hi(g4.w);
;                 if (ADD) { const u32x4 o = oo[m][bj];
;                     v0[0] += bf_lo(o.x); v0[1] += bf_hi(o.x); v0[2] += bf_lo(o.y); v0[3] += bf_hi(o.y); v1[0] += bf_lo(o.z); v1[1] += bf_hi(o.z); v1[2] += bf_lo(o.w); v1[3] += bf_hi(o.w); }
;                 *(u32x4*)(O + off) = pack8(v0, v1); }
	v_add_u32_e32 v134, 0x80, v210
	v_ashrrev_i32_e32 v135, 31, v134
	v_lshlrev_b32_e32 v74, 16, v150
	v_and_b32_e32 v75, 0xffff0000, v150
	v_lshlrev_b32_e32 v76, 16, v146
	v_and_b32_e32 v77, 0xffff0000, v146
	v_pk_fma_f32 v[70:71], v[70:71], v[74:75], v[76:77]
	v_lshlrev_b32_e32 v74, 16, v151
	v_and_b32_e32 v75, 0xffff0000, v151
	v_lshlrev_b32_e32 v76, 16, v147
	v_and_b32_e32 v77, 0xffff0000, v147
	v_pk_fma_f32 v[72:73], v[72:73], v[74:75], v[76:77]
	v_lshlrev_b32_e32 v74, 16, v152
	v_and_b32_e32 v75, 0xffff0000, v152
	v_lshlrev_b32_e32 v76, 16, v148
	v_and_b32_e32 v77, 0xffff0000, v148
	v_pk_fma_f32 v[74:75], v[66:67], v[74:75], v[76:77]
	v_lshlrev_b32_e32 v66, 16, v153
	v_and_b32_e32 v67, 0xffff0000, v153
	v_lshlrev_b32_e32 v76, 16, v149
	v_and_b32_e32 v77, 0xffff0000, v149
	v_pk_fma_f32 v[76:77], v[68:69], v[66:67], v[76:77]
	v_cvt_pk_bf16_f32 v66, v70, v71
	v_cvt_pk_bf16_f32 v67, v72, v73
	v_cvt_pk_bf16_f32 v68, v74, v75
	v_cvt_pk_bf16_f32 v69, v76, v77
	global_store_dwordx4 v[78:79], v[66:69], off offset:256
	v_add_u32_e32 v136, 0x90, v210
	v_ashrrev_i32_e32 v137, 31, v136
	v_lshlrev_b64 v[66:67], 10, v[134:135]
	v_lshl_add_u64 v[66:67], v[66:67], 0, s[22:23]
	v_or_b32_e32 v68, v66, v202
	v_mov_b32_e32 v69, v67
	v_lshlrev_b64 v[68:69], 1, v[68:69]
	v_lshl_add_u64 v[70:71], s[6:7], 0, v[68:69]
	v_lshl_add_u64 v[68:69], s[8:9], 0, v[68:69]
	global_load_dwordx4 v[110:113], v[70:71], off
	global_load_dwordx4 v[114:117], v[68:69], off
	v_or_b32_e32 v66, v66, v204
	v_lshlrev_b64 v[66:67], 1, v[66:67]
	v_lshl_add_u64 v[68:69], s[6:7], 0, v[66:67]
	v_lshl_add_u64 v[66:67], s[8:9], 0, v[66:67]
	global_load_dwordx4 v[118:121], v[68:69], off
	global_load_dwordx4 v[122:125], v[66:67], off
	v_lshlrev_b64 v[66:67], 10, v[136:137]
	v_lshl_add_u64 v[66:67], v[66:67], 0, s[22:23]
	v_or_b32_e32 v68, v66, v202
	v_mov_b32_e32 v69, v67
	v_lshlrev_b64 v[68:69], 1, v[68:69]
	v_lshl_add_u64 v[70:71], s[6:7], 0, v[68:69]
	v_lshl_add_u64 v[68:69], s[8:9], 0, v[68:69]
	global_load_dwordx4 v[126:129], v[70:71], off
	global_load_dwordx4 v[130:133], v[68:69], off
	v_or_b32_e32 v66, v66, v204
	v_lshlrev_b64 v[66:67], 1, v[66:67]
	v_lshl_add_u64 v[68:69], s[6:7], 0, v[66:67]
	v_lshl_add_u64 v[66:67], s[8:9], 0, v[66:67]
	global_load_dwordx4 v[98:101], v[68:69], off
	global_load_dwordx4 v[102:105], v[66:67], off
	v_lshlrev_b64 v[66:67], 10, v[108:109]
	v_lshl_add_u64 v[66:67], v[66:67], 0, s[22:23]
	v_or_b32_e32 v68, v66, v202
	v_mov_b32_e32 v69, v67
	v_lshlrev_b64 v[68:69], 1, v[68:69]
	v_lshl_add_u64 v[70:71], s[6:7], 0, v[68:69]
	v_lshl_add_u64 v[68:69], s[8:9], 0, v[68:69]
	global_load_dwordx4 v[90:93], v[70:71], off
	global_load_dwordx4 v[94:97], v[68:69], off
	v_or_b32_e32 v66, v66, v204
	v_lshlrev_b64 v[66:67], 1, v[66:67]
	v_lshl_add_u64 v[68:69], s[6:7], 0, v[66:67]
	v_lshl_add_u64 v[66:67], s[8:9], 0, v[66:67]
	v_add_u32_e32 v106, 0xb0, v210
	global_load_dwordx4 v[82:85], v[68:69], off
	global_load_dwordx4 v[86:89], v[66:67], off
	v_ashrrev_i32_e32 v107, 31, v106
	v_lshlrev_b64 v[66:67], 10, v[106:107]
	v_lshl_add_u64 v[66:67], v[66:67], 0, s[22:23]
	v_or_b32_e32 v68, v66, v202
	v_mov_b32_e32 v69, v67
	v_lshlrev_b64 v[68:69], 1, v[68:69]
	v_lshl_add_u64 v[70:71], s[6:7], 0, v[68:69]
	v_lshl_add_u64 v[68:69], s[8:9], 0, v[68:69]
	global_load_dwordx4 v[74:77], v[70:71], off
	global_load_dwordx4 v[78:81], v[68:69], off
	v_or_b32_e32 v66, v66, v204
	v_lshlrev_b64 v[70:71], 1, v[66:67]
	v_lshl_add_u64 v[66:67], s[6:7], 0, v[70:71]
	v_lshl_add_u64 v[70:71], s[8:9], 0, v[70:71]
	global_load_dwordx4 v[66:69], v[66:67], off
	v_lshlrev_b64 v[134:135], 11, v[134:135]
	global_load_dwordx4 v[70:73], v[70:71], off
	s_waitcnt vmcnt(15)
	v_lshlrev_b32_e32 v138, 16, v110
	v_and_b32_e32 v139, 0xffff0000, v110
	s_waitcnt vmcnt(14)
	v_lshlrev_b32_e32 v140, 16, v114
	v_and_b32_e32 v141, 0xffff0000, v114
	v_lshlrev_b32_e32 v110, 16, v111
	v_and_b32_e32 v111, 0xffff0000, v111
	v_lshlrev_b32_e32 v114, 16, v115
	v_and_b32_e32 v115, 0xffff0000, v115
	v_pk_fma_f32 v[64:65], v[64:65], v[110:111], v[114:115]
	v_lshlrev_b32_e32 v110, 16, v112
	v_and_b32_e32 v111, 0xffff0000, v112
	v_lshlrev_b32_e32 v114, 16, v116
	v_and_b32_e32 v115, 0xffff0000, v116
	v_pk_fma_f32 v[62:63], v[62:63], v[138:139], v[140:141]
	v_pk_fma_f32 v[110:111], v[58:59], v[110:111], v[114:115]
	v_lshlrev_b32_e32 v58, 16, v113
	v_and_b32_e32 v59, 0xffff0000, v113
	v_lshlrev_b32_e32 v112, 16, v117
	v_and_b32_e32 v113, 0xffff0000, v117
	v_pk_fma_f32 v[112:113], v[60:61], v[58:59], v[112:113]
	v_cvt_pk_bf16_f32 v58, v62, v63
	v_lshl_add_u64 v[62:63], s[8:9], 0, v[134:135]
	v_lshl_add_u64 v[62:63], v[62:63], 0, s[24:25]
	v_cvt_pk_bf16_f32 v59, v64, v65
	v_cvt_pk_bf16_f32 v60, v110, v111
	v_cvt_pk_bf16_f32 v61, v112, v113
	v_lshl_add_u64 v[62:63], v[62:63], 0, v[0:1]
	global_store_dwordx4 v[62:63], v[58:61], off
	s_waitcnt vmcnt(14)
	s_nop 0
	v_lshlrev_b32_e32 v58, 16, v118
	v_and_b32_e32 v59, 0xffff0000, v118
	s_waitcnt vmcnt(13)
	v_lshlrev_b32_e32 v60, 16, v122
	v_and_b32_e32 v61, 0xffff0000, v122
	v_pk_fma_f32 v[54:55], v[54:55], v[58:59], v[60:61]
	v_lshlrev_b32_e32 v58, 16, v119
	v_and_b32_e32 v59, 0xffff0000, v119
	v_lshlrev_b32_e32 v60, 16, v123
	v_and_b32_e32 v61, 0xffff0000, v123
	v_pk_fma_f32 v[56:57], v[56:57], v[58:59], v[60:61]
	v_lshlrev_b32_e32 v58, 16, v120
	v_and_b32_e32 v59, 0xffff0000, v120
	v_lshlrev_b32_e32 v60, 16, v124
	v_and_b32_e32 v61, 0xffff0000, v124
	v_pk_fma_f32 v[58:59], v[50:51], v[58:59], v[60:61]
	v_lshlrev_b32_e32 v50, 16, v121
	v_and_b32_e32 v51, 0xffff0000, v121
	v_lshlrev_b32_e32 v60, 16, v125
	v_and_b32_e32 v61, 0xffff0000, v125
	v_pk_fma_f32 v[60:61], v[52:53], v[50:51], v[60:61]
	v_cvt_pk_bf16_f32 v50, v54, v55
	v_cvt_pk_bf16_f32 v51, v56, v57
	v_cvt_pk_bf16_f32 v52, v58, v59
	v_cvt_pk_bf16_f32 v53, v60, v61
	global_store_dwordx4 v[62:63], v[50:53], off offset:256
	s_waitcnt vmcnt(12)
; __device__ __forceinline__ u32x4 pack8(const f32x4 v0, const f32x4 v1) { u32x4 w; w.x = cvt_pk_bf16(v0[0], v0[1]); w.y = cvt_pk_bf16(v0[2], v0[3]); w.z = cvt_pk_bf16(v1[0], v1[1]); w.w = cvt_pk_bf16(v1[2], v1[3]); return w; }
; __device__ __forceinline__ float bf_lo(unsigned w) { return __uint_as_float(w << 16); }
; __device__ __forceinline__ float bf_hi(unsigned w) { return __uint_as_float(w & 0xffff0000u); }
;     __device__ __forceinline__ void operator()(const f32x4 (&acc)[2][2][4][2], const Unit& u, int wr, int wc, int fr, int fq) const {
;         _Pragma("unroll") for (int ai = 0; ai < 2; ++ai) {
;             u32x4 gt[4][2], oo[4][2];
;             _Pragma("unroll") for (int m = 0; m < 4; ++m) _Pragma("unroll") for (int bj = 0; bj < 2; ++bj) { const size_t off = (size_t)EPI_ROW(ai, m) * 1024 + u.pn * BM + EPI_CT(bj);
;                 gt[m][bj] = *(const u32x4*)(G + off); if (ADD) oo[m][bj] = *(const u32x4*)(O + off); }
;             _Pragma("unroll") for (int m = 0; m < 4; ++m) _Pragma("unroll") for (int bj = 0; bj < 2; ++bj) { const size_t off = (size_t)EPI_ROW(ai, m) * 1024 + u.pn * BM + EPI_CT(bj);
;                 f32x4 v0 = acc[ai][bj][m][0], v1 = acc[ai][bj][m][1]; const u32x4 g4 = gt[m][bj];
;                 v0[0] *= bf_lo(g4.x); v0[1] *= bf_hi(g4.x); v0[2] *= bf_lo(g4.y); v0[3] *= bf_hi(g4.y); v1[0] *= bf_lo(g4.z); v1[1] *= bf_hi(g4.z); v1[2] *= bf_lo(g4.w); v1[3] *= bf_hi(g4.w);
;                 if (ADD) { const u32x4 o = oo[m][bj];
;                     v0[0] += bf_lo(o.x); v0[1] += bf_hi(o.x); v0[2] += bf_lo(o.y); v0[3] += bf_hi(o.y); v1[0] += bf_lo(o.z); v1[1] += bf_hi(o.z); v1[2] += bf_lo(o.w); v1[3] += bf_hi(o.w); }
;                 *(u32x4*)(O + off) = pack8(v0, v1); }
	v_lshlrev_b32_e32 v54, 16, v130
	v_and_b32_e32 v55, 0xffff0000, v130
	v_lshlrev_b32_e32 v52, 16, v126
	v_and_b32_e32 v53, 0xffff0000, v126
	v_pk_fma_f32 v[46:47], v[46:47], v[52:53], v[54:55]
	v_lshlrev_b32_e32 v52, 16, v127
	v_and_b32_e32 v53, 0xffff0000, v127
	v_lshlrev_b32_e32 v54, 16, v131
	v_and_b32_e32 v55, 0xffff0000, v131
	v_pk_fma_f32 v[48:49], v[48:49], v[52:53], v[54:55]
	v_lshlrev_b32_e32 v52, 16, v128
	v_and_b32_e32 v53, 0xffff0000, v128
	v_lshlrev_b32_e32 v54, 16, v132
	v_and_b32_e32 v55, 0xffff0000, v132
	v_lshlrev_b64 v[50:51], 11, v[136:137]
	v_pk_fma_f32 v[52:53], v[42:43], v[52:53], v[54:55]
	v_lshlrev_b32_e32 v42, 16, v129
	v_and_b32_e32 v43, 0xffff0000, v129
	v_lshlrev_b32_e32 v54, 16, v133
	v_and_b32_e32 v55, 0xffff0000, v133
	v_pk_fma_f32 v[54:55], v[44:45], v[42:43], v[54:55]
	v_cvt_pk_bf16_f32 v42, v46, v47
	v_lshl_add_u64 v[46:47], s[8:9], 0, v[50:51]
	v_lshl_add_u64 v[46:47], v[46:47], 0, s[24:25]
	v_cvt_pk_bf16_f32 v43, v48, v49
	v_cvt_pk_bf16_f32 v44, v52, v53
	v_cvt_pk_bf16_f32 v45, v54, v55
	v_lshl_add_u64 v[46:47], v[46:47], 0, v[0:1]
	global_store_dwordx4 v[46:47], v[42:45], off
	s_waitcnt vmcnt(12)
	s_nop 0
	v_lshlrev_b32_e32 v42, 16, v98
	v_and_b32_e32 v43, 0xffff0000, v98
	s_waitcnt vmcnt(11)
	v_lshlrev_b32_e32 v44, 16, v102
	v_and_b32_e32 v45, 0xffff0000, v102
	v_pk_fma_f32 v[38:39], v[38:39], v[42:43], v[44:45]
	v_lshlrev_b32_e32 v42, 16, v99
	v_and_b32_e32 v43, 0xffff0000, v99
	v_lshlrev_b32_e32 v44, 16, v103
	v_and_b32_e32 v45, 0xffff0000, v103
	v_pk_fma_f32 v[40:41], v[40:41], v[42:43], v[44:45]
	v_lshlrev_b32_e32 v42, 16, v100
	v_and_b32_e32 v43, 0xffff0000, v100
	v_lshlrev_b32_e32 v44, 16, v104
	v_and_b32_e32 v45, 0xffff0000, v104
	v_pk_fma_f32 v[42:43], v[34:35], v[42:43], v[44:45]
	v_lshlrev_b32_e32 v34, 16, v101
	v_and_b32_e32 v35, 0xffff0000, v101
	v_lshlrev_b32_e32 v44, 16, v105
	v_and_b32_e32 v45, 0xffff0000, v105
	v_pk_fma_f32 v[44:45], v[36:37], v[34:35], v[44:45]
	v_cvt_pk_bf16_f32 v34, v38, v39
	v_cvt_pk_bf16_f32 v35, v40, v41
	v_cvt_pk_bf16_f32 v36, v42, v43
	v_cvt_pk_bf16_f32 v37, v44, v45
	global_store_dwordx4 v[46:47], v[34:37], off offset:256
	s_waitcnt vmcnt(10)
	v_lshlrev_b32_e32 v38, 16, v94
	v_and_b32_e32 v39, 0xffff0000, v94
	v_lshlrev_b32_e32 v36, 16, v90
	v_and_b32_e32 v37, 0xffff0000, v90
	v_pk_fma_f32 v[30:31], v[30:31], v[36:37], v[38:39]
	v_lshlrev_b32_e32 v36, 16, v91
	v_and_b32_e32 v37, 0xffff0000, v91
	v_lshlrev_b32_e32 v38, 16, v95
	v_and_b32_e32 v39, 0xffff0000, v95
	v_pk_fma_f32 v[32:33], v[32:33], v[36:37], v[38:39]
	v_lshlrev_b32_e32 v36, 16, v92
	v_and_b32_e32 v37, 0xffff0000, v92
	v_lshlrev_b32_e32 v38, 16, v96
	v_and_b32_e32 v39, 0xffff0000, v96
	v_lshlrev_b64 v[34:35], 11, v[108:109]
	v_pk_fma_f32 v[36:37], v[26:27], v[36:37], v[38:39]
	v_lshlrev_b32_e32 v26, 16, v93
	v_and_b32_e32 v27, 0xffff0000, v93
	v_lshlrev_b32_e32 v38, 16, v97
	v_and_b32_e32 v39, 0xffff0000, v97
	v_pk_fma_f32 v[38:39], v[28:29], v[26:27], v[38:39]
	v_cvt_pk_bf16_f32 v26, v30, v31
	v_lshl_add_u64 v[30:31], s[8:9], 0, v[34:35]
	v_lshl_add_u64 v[30:31], v[30:31], 0, s[24:25]
	v_cvt_pk_bf16_f32 v27, v32, v33
	v_cvt_pk_bf16_f32 v28, v36, v37
	v_cvt_pk_bf16_f32 v29, v38, v39
	v_lshl_add_u64 v[30:31], v[30:31], 0, v[0:1]
	global_store_dwordx4 v[30:31], v[26:29], off
	s_waitcnt vmcnt(10)
	s_nop 0
	v_lshlrev_b32_e32 v26, 16, v82
	v_and_b32_e32 v27, 0xffff0000, v82
	s_waitcnt vmcnt(9)
	v_lshlrev_b32_e32 v28, 16, v86
	v_and_b32_e32 v29, 0xffff0000, v86
	v_pk_fma_f32 v[22:23], v[22:23], v[26:27], v[28:29]
	v_lshlrev_b32_e32 v26, 16, v83
	v_and_b32_e32 v27, 0xffff0000, v83
	v_lshlrev_b32_e32 v28, 16, v87
	v_and_b32_e32 v29, 0xffff0000, v87
	v_pk_fma_f32 v[24:25], v[24:25], v[26:27], v[28:29]
	v_lshlrev_b32_e32 v26, 16, v84
	v_and_b32_e32 v27, 0xffff0000, v84
	v_lshlrev_b32_e32 v28, 16, v88
	v_and_b32_e32 v29, 0xffff0000, v88
	v_pk_fma_f32 v[26:27], v[18:19], v[26:27], v[28:29]
	v_lshlrev_b32_e32 v18, 16, v85
	v_and_b32_e32 v19, 0xffff0000, v85
	v_lshlrev_b32_e32 v28, 16, v89
	v_and_b32_e32 v29, 0xffff0000, v89
	v_pk_fma_f32 v[28:29], v[20:21], v[18:19], v[28:29]
	v_cvt_pk_bf16_f32 v18, v22, v23
	v_cvt_pk_bf16_f32 v19, v24, v25
	v_cvt_pk_bf16_f32 v20, v26, v27
	v_cvt_pk_bf16_f32 v21, v28, v29
	global_store_dwordx4 v[30:31], v[18:21], off offset:256
	s_waitcnt vmcnt(8)
	v_lshlrev_b32_e32 v22, 16, v78
	v_and_b32_e32 v23, 0xffff0000, v78
	v_lshlrev_b32_e32 v20, 16, v74
	v_and_b32_e32 v21, 0xffff0000, v74
	v_pk_fma_f32 v[14:15], v[14:15], v[20:21], v[22:23]
	v_lshlrev_b32_e32 v20, 16, v75
	v_and_b32_e32 v21, 0xffff0000, v75
	v_lshlrev_b32_e32 v22, 16, v79
	v_and_b32_e32 v23, 0xffff0000, v79
	v_pk_fma_f32 v[16:17], v[16:17], v[20:21], v[22:23]
	v_lshlrev_b32_e32 v20, 16, v76
	v_and_b32_e32 v21, 0xffff0000, v76
	v_lshlrev_b32_e32 v22, 16, v80
	v_and_b32_e32 v23, 0xffff0000, v80
	v_lshlrev_b64 v[18:19], 11, v[106:107]
	v_pk_fma_f32 v[20:21], v[10:11], v[20:21], v[22:23]
	v_lshlrev_b32_e32 v10, 16, v77
	v_and_b32_e32 v11, 0xffff0000, v77
	v_lshlrev_b32_e32 v22, 16, v81
	v_and_b32_e32 v23, 0xffff0000, v81
	v_pk_fma_f32 v[22:23], v[12:13], v[10:11], v[22:23]
	v_cvt_pk_bf16_f32 v10, v14, v15
	v_lshl_add_u64 v[14:15], s[8:9], 0, v[18:19]
	v_lshl_add_u64 v[14:15], v[14:15], 0, s[24:25]
	v_cvt_pk_bf16_f32 v11, v16, v17
	v_cvt_pk_bf16_f32 v12, v20, v21
	v_cvt_pk_bf16_f32 v13, v22, v23
	v_lshl_add_u64 v[14:15], v[14:15], 0, v[0:1]
	global_store_dwordx4 v[14:15], v[10:13], off
	s_waitcnt vmcnt(8)
	s_nop 0
	v_lshlrev_b32_e32 v10, 16, v66
	v_and_b32_e32 v11, 0xffff0000, v66
	s_waitcnt vmcnt(7)
	v_lshlrev_b32_e32 v12, 16, v70
	v_and_b32_e32 v13, 0xffff0000, v70
	v_pk_fma_f32 v[6:7], v[6:7], v[10:11], v[12:13]
	v_lshlrev_b32_e32 v10, 16, v67
	v_and_b32_e32 v11, 0xffff0000, v67
	v_lshlrev_b32_e32 v12, 16, v71
	v_and_b32_e32 v13, 0xffff0000, v71
	v_pk_fma_f32 v[8:9], v[8:9], v[10:11], v[12:13]
	v_lshlrev_b32_e32 v10, 16, v68
	v_and_b32_e32 v11, 0xffff0000, v68
	v_lshlrev_b32_e32 v12, 16, v72
	v_and_b32_e32 v13, 0xffff0000, v72
	v_pk_fma_f32 v[10:11], v[2:3], v[10:11], v[12:13]
	v_lshlrev_b32_e32 v2, 16, v69
	v_and_b32_e32 v3, 0xffff0000, v69
	v_lshlrev_b32_e32 v12, 16, v73
	v_and_b32_e32 v13, 0xffff0000, v73
	v_pk_fma_f32 v[12:13], v[4:5], v[2:3], v[12:13]
	v_cvt_pk_bf16_f32 v2, v6, v7
	v_cvt_pk_bf16_f32 v3, v8, v9
	v_cvt_pk_bf16_f32 v4, v10, v11
	v_cvt_pk_bf16_f32 v5, v12, v13
	global_store_dwordx4 v[14:15], v[2:5], off offset:256
	s_cbranch_vccnz .LBB0_624
	s_andn2_b64 vcc, exec, s[0:1]
	s_cbranch_vccnz .LBB0_623
	s_branch .LBB0_623
